# attention v2 (16B mask loads every other tile, static prio for waves 4-7) + hand-written weight conversion
# speedup vs baseline: 1.0273x; 1.0052x over previous
.LBB0_786:
	v_lshrrev_b32_e32 v235, 6, v186
	v_and_b32_e32 v236, 63, v186
	v_readfirstlane_b32 s3, v235
	v_and_b32_e32 v237, 31, v236
	v_lshrrev_b32_e32 v238, 5, v236
	v_lshlrev_b32_e32 v229, 2, v238
	v_lshrrev_b32_e32 v239, 3, v186
	v_and_b32_e32 v240, 7, v186
	v_mul_u32_u24_e32 v33, 0x2cb0, v239
	v_bfe_u32 v241, v239, 1, 3
	v_xor_b32_e32 v241, v240, v241
	v_lshl_add_u32 v221, v241, 4, v33
	v_add_u32_e32 v221, 0x400, v221
	v_bfe_u32 v241, v239, 1, 1
	v_lshlrev_b32_e32 v241, 2, v241
	v_xor_b32_e32 v241, v240, v241
	v_lshl_add_u32 v222, v241, 4, v33
	v_add_u32_e32 v222, 0x800, v222
	v_bfe_u32 v241, v237, 1, 3
	v_or_b32_e32 v242, 0, v238
	v_xor_b32_e32 v242, v242, v241
	v_lshlrev_b32_e32 v242, 4, v242
	v_lshl_add_u32 v223, v237, 7, v242
	v_or_b32_e32 v242, 2, v238
	v_xor_b32_e32 v242, v242, v241
	v_lshlrev_b32_e32 v242, 4, v242
	v_lshl_add_u32 v224, v237, 7, v242
	v_or_b32_e32 v242, 4, v238
	v_xor_b32_e32 v242, v242, v241
	v_lshlrev_b32_e32 v242, 4, v242
	v_lshl_add_u32 v225, v237, 7, v242
	v_or_b32_e32 v242, 6, v238
	v_xor_b32_e32 v242, v242, v241
	v_lshlrev_b32_e32 v242, 4, v242
	v_lshl_add_u32 v226, v237, 7, v242
	v_and_b32_e32 v239, 3, v236
	v_bfe_u32 v240, v236, 2, 2
	v_bfe_u32 v241, v236, 4, 1
	v_lshrrev_b32_e32 v242, 1, v239
	v_lshl_add_u32 v241, v241, 1, v242
	v_lshrrev_b32_e32 v242, 1, v240
	v_lshl_add_u32 v33, v242, 2, v241
	v_xor_b32_e32 v242, 1, v242
	v_lshl_add_u32 v197, v242, 2, v241
	v_lshl_add_u32 v240, v238, 2, v240
	v_and_b32_e32 v239, 1, v239
	v_lshlrev_b32_e32 v239, 3, v239
	v_lshl_add_u32 v240, v240, 7, v239
	v_lshl_add_u32 v227, v33, 4, v240
	v_lshl_add_u32 v228, v197, 4, v240
	v_add_u32_e32 v227, 0x8000, v227
	v_add_u32_e32 v228, 0x8000, v228
	s_lshl_b32 s58, s3, 10
	s_cmp_lt_u32 s3, 4
	s_cbranch_scc1 .Lat_noprio
	s_setprio 1
.Lat_noprio:
	v_readlane_b32 s18, v252, 26
	s_and_b32 s19, s84, 7
	s_cmp_lg_u32 s19, 0
	s_mov_b32 s0, s18
	s_cbranch_scc1 .Lat_item
	s_and_b32 s19, s18, 7
	s_lshr_b32 s0, s84, 3
	s_mul_i32 s0, s19, s0
	s_lshr_b32 s19, s18, 3
	s_add_u32 s0, s0, s19

.Lat_qb:
	s_lshl_b32 s9, s2, 2
	s_lshr_b32 s10, s3, 1
	s_add_u32 s10, s10, s9
	s_add_u32 s11, s9, 3
	s_add_u32 s9, s9, 4
	s_lshl_b32 s18, s2, 8
	s_lshl_b32 s19, s3, 5
	s_add_u32 s18, s18, s19
	v_and_b32_e32 v235, 31, v186
	v_bfe_u32 v237, v186, 5, 1
	v_add_u32_e32 v235, s18, v235
	v_lshlrev_b32_e32 v219, 10, v235
	v_mul_u32_u24_e32 v236, 0x2cb0, v235
	v_lshl_add_u32 v220, v237, 4, v236
	v_lshl_add_u32 v197, v237, 3, v236
	global_load_dwordx4 v[102:105], v220, s[4:5] offset:0
	global_load_dwordx4 v[106:109], v220, s[4:5] offset:32
	global_load_dwordx4 v[110:113], v220, s[4:5] offset:64
	global_load_dwordx4 v[114:117], v220, s[4:5] offset:96
	s_mov_b64 s[12:13], s[4:5]
	s_add_i32 m0, s58, 0x0
	s_nop 0
	global_load_lds_dwordx4 v221, s[12:13]
	s_add_i32 m0, s58, 0x8000
	s_nop 0
	global_load_lds_dwordx4 v222, s[12:13]
	s_add_u32 s12, s12, 0xb2c00
	s_addc_u32 s13, s13, 0
	s_add_i32 m0, s58, 0x2000
	s_nop 0
	global_load_lds_dwordx4 v221, s[12:13]
	s_add_u32 s12, s12, 0xb2c00
	s_addc_u32 s13, s13, 0
	s_add_i32 m0, s58, 0x4000
	s_nop 0
	global_load_lds_dwordx4 v221, s[12:13]
	s_add_u32 s12, s12, 0xb2c00
	s_addc_u32 s13, s13, 0
	global_load_dwordx4 v[198:201], v219, s[6:7]
	s_add_i32 m0, s58, 0x6000
	s_nop 0
	global_load_lds_dwordx4 v221, s[12:13]
	s_add_u32 s14, s4, 0xb2c00
	s_addc_u32 s15, s5, 0
	s_add_i32 m0, s58, 0xa000
	s_nop 0
	global_load_lds_dwordx4 v222, s[14:15]
	v_mov_b32_e32 v230, 0xff800000
	v_mov_b32_e32 v231, 0
	v_mov_b32_e32 v0, 0
	v_mov_b32_e32 v1, 0
	v_mov_b32_e32 v2, 0
	v_mov_b32_e32 v3, 0
	v_mov_b32_e32 v4, 0
	v_mov_b32_e32 v5, 0
	v_mov_b32_e32 v6, 0
	v_mov_b32_e32 v7, 0
	v_mov_b32_e32 v8, 0
	v_mov_b32_e32 v9, 0
	v_mov_b32_e32 v10, 0
	v_mov_b32_e32 v11, 0
	v_mov_b32_e32 v12, 0
	v_mov_b32_e32 v13, 0
	v_mov_b32_e32 v14, 0
	v_mov_b32_e32 v15, 0
	v_mov_b32_e32 v16, 0
	v_mov_b32_e32 v17, 0
	v_mov_b32_e32 v18, 0
	v_mov_b32_e32 v19, 0
	v_mov_b32_e32 v20, 0
	v_mov_b32_e32 v21, 0
	v_mov_b32_e32 v22, 0
	v_mov_b32_e32 v23, 0
	v_mov_b32_e32 v24, 0
	v_mov_b32_e32 v25, 0
	v_mov_b32_e32 v26, 0
	v_mov_b32_e32 v27, 0
	v_mov_b32_e32 v28, 0
	v_mov_b32_e32 v29, 0
	v_mov_b32_e32 v30, 0
	v_mov_b32_e32 v31, 0
	s_waitcnt vmcnt(2)
	s_barrier
	ds_read_b128 v[118:121], v223 offset:0
	ds_read_b128 v[122:125], v223 offset:4096
	ds_read_b128 v[126:129], v224 offset:0
	ds_read_b128 v[130:133], v224 offset:4096
	ds_read_b128 v[134:137], v225 offset:0
	ds_read_b128 v[138:141], v225 offset:4096
	ds_read_b128 v[142:145], v226 offset:0
	ds_read_b128 v[146:149], v226 offset:4096
	s_waitcnt lgkmcnt(0)
	s_barrier
	v_mfma_f32_32x32x16_bf16 v[34:49], v[118:121], v[102:105], 0
	v_mfma_f32_32x32x16_bf16 v[50:65], v[122:125], v[102:105], 0
	v_mfma_f32_32x32x16_bf16 v[34:49], v[126:129], v[106:109], v[34:49]
	v_mfma_f32_32x32x16_bf16 v[50:65], v[130:133], v[106:109], v[50:65]
	v_mfma_f32_32x32x16_bf16 v[34:49], v[134:137], v[110:113], v[34:49]
	v_mfma_f32_32x32x16_bf16 v[50:65], v[138:141], v[110:113], v[50:65]
	v_mfma_f32_32x32x16_bf16 v[34:49], v[142:145], v[114:117], v[34:49]
	v_mfma_f32_32x32x16_bf16 v[50:65], v[146:149], v[114:117], v[50:65]
	ds_read_b128 v[118:121], v223 offset:8192
	ds_read_b128 v[122:125], v223 offset:12288
	ds_read_b128 v[126:129], v224 offset:8192
	ds_read_b128 v[130:133], v224 offset:12288
	ds_read_b128 v[134:137], v225 offset:8192
	ds_read_b128 v[138:141], v225 offset:12288
	ds_read_b128 v[142:145], v226 offset:8192
	ds_read_b128 v[146:149], v226 offset:12288
	s_waitcnt lgkmcnt(14)
	s_mov_b32 s8, 0
	s_nop 7
	v_lshrrev_b32_e32 v249, v229, v198
	v_lshrrev_b32_e32 v250, v229, v199
	v_bfe_i32 v235, v249, 0, 1
	v_bfe_i32 v236, v250, 0, 1
	v_bfe_i32 v237, v249, 1, 1
	v_bfe_i32 v238, v250, 1, 1
	v_bfe_i32 v239, v249, 2, 1
	v_bfe_i32 v240, v250, 2, 1
	v_bfe_i32 v241, v249, 3, 1
	v_bfe_i32 v242, v250, 3, 1
	v_bitop3_b32 v34, v34, s33, v235 bitop3:0xe4
	v_bitop3_b32 v50, v50, s33, v236 bitop3:0xe4
	v_bitop3_b32 v35, v35, s33, v237 bitop3:0xe4
	v_bitop3_b32 v51, v51, s33, v238 bitop3:0xe4
	v_bitop3_b32 v36, v36, s33, v239 bitop3:0xe4
	v_bitop3_b32 v52, v52, s33, v240 bitop3:0xe4
	v_bitop3_b32 v37, v37, s33, v241 bitop3:0xe4
	v_bitop3_b32 v53, v53, s33, v242 bitop3:0xe4
	v_max3_f32 v247, v34, s33, v50
	v_max3_f32 v248, v35, s33, v51
	v_max3_f32 v247, v247, v36, v52
	v_max3_f32 v248, v248, v37, v53
	v_bfe_i32 v235, v249, 8, 1
	v_bfe_i32 v236, v250, 8, 1
	v_bfe_i32 v237, v249, 9, 1
	v_bfe_i32 v238, v250, 9, 1
	v_bfe_i32 v239, v249, 10, 1
	v_bfe_i32 v240, v250, 10, 1
	v_bfe_i32 v241, v249, 11, 1
	v_bfe_i32 v242, v250, 11, 1
	v_bitop3_b32 v38, v38, s33, v235 bitop3:0xe4
	v_bitop3_b32 v54, v54, s33, v236 bitop3:0xe4
	v_bitop3_b32 v39, v39, s33, v237 bitop3:0xe4
	v_bitop3_b32 v55, v55, s33, v238 bitop3:0xe4
	v_bitop3_b32 v40, v40, s33, v239 bitop3:0xe4
	v_bitop3_b32 v56, v56, s33, v240 bitop3:0xe4
	v_bitop3_b32 v41, v41, s33, v241 bitop3:0xe4
	v_bitop3_b32 v57, v57, s33, v242 bitop3:0xe4
	v_max3_f32 v247, v247, v38, v54
	v_max3_f32 v248, v248, v39, v55
	v_max3_f32 v247, v247, v40, v56
	v_max3_f32 v248, v248, v41, v57
	v_bfe_i32 v235, v249, 16, 1
	v_bfe_i32 v236, v250, 16, 1
	v_bfe_i32 v237, v249, 17, 1
	v_bfe_i32 v238, v250, 17, 1
	v_bfe_i32 v239, v249, 18, 1
	v_bfe_i32 v240, v250, 18, 1
	v_bfe_i32 v241, v249, 19, 1
	v_bfe_i32 v242, v250, 19, 1
	v_bitop3_b32 v42, v42, s33, v235 bitop3:0xe4
	v_bitop3_b32 v58, v58, s33, v236 bitop3:0xe4
	v_bitop3_b32 v43, v43, s33, v237 bitop3:0xe4
	v_bitop3_b32 v59, v59, s33, v238 bitop3:0xe4
	v_bitop3_b32 v44, v44, s33, v239 bitop3:0xe4
	v_bitop3_b32 v60, v60, s33, v240 bitop3:0xe4
	v_bitop3_b32 v45, v45, s33, v241 bitop3:0xe4
	v_bitop3_b32 v61, v61, s33, v242 bitop3:0xe4
	v_max3_f32 v247, v247, v42, v58
	v_max3_f32 v248, v248, v43, v59
	v_max3_f32 v247, v247, v44, v60
	v_max3_f32 v248, v248, v45, v61
	v_bfe_i32 v235, v249, 24, 1
	v_bfe_i32 v236, v250, 24, 1
	v_bfe_i32 v237, v249, 25, 1
	v_bfe_i32 v238, v250, 25, 1
	v_bfe_i32 v239, v249, 26, 1
	v_bfe_i32 v240, v250, 26, 1
	v_bfe_i32 v241, v249, 27, 1
	v_bfe_i32 v242, v250, 27, 1
	v_bitop3_b32 v46, v46, s33, v235 bitop3:0xe4
	v_bitop3_b32 v62, v62, s33, v236 bitop3:0xe4
	v_bitop3_b32 v47, v47, s33, v237 bitop3:0xe4
	v_bitop3_b32 v63, v63, s33, v238 bitop3:0xe4
	v_bitop3_b32 v48, v48, s33, v239 bitop3:0xe4
	v_bitop3_b32 v64, v64, s33, v240 bitop3:0xe4
	v_bitop3_b32 v49, v49, s33, v241 bitop3:0xe4
	v_bitop3_b32 v65, v65, s33, v242 bitop3:0xe4
	v_max3_f32 v247, v247, v46, v62
	v_max3_f32 v248, v248, v47, v63
	v_max3_f32 v247, v247, v48, v64
	v_max3_f32 v248, v248, v49, v65
	v_max_f32_e32 v247, v247, v248
	v_mov_b32_e32 v248, v247
	s_nop 1
	v_permlane32_swap_b32_e32 v247, v248
	v_max3_f32 v247, v230, v247, v248
	v_cmp_neq_f32_e32 vcc, s33, v247
	s_nop 1
	v_cndmask_b32_e32 v248, 0, v247, vcc
	v_sub_f32_e32 v33, v230, v248
	v_mul_f32_e32 v33, 0x3e38aa3b, v33
	v_exp_f32_e32 v232, v33
	v_mul_f32_e32 v234, 0xbe38aa3b, v248
	v_mov_b32_e32 v230, v247
.Lat_loop_0:
	s_add_u32 s18, s8, 4
	s_min_u32 s18, s18, s11
	s_mul_i32 s18, s18, 0xb2c00
	s_add_u32 s12, s4, s18
	s_addc_u32 s13, s5, 0
	s_add_u32 s19, s8, 2
	s_min_u32 s19, s19, s11
	s_mul_i32 s18, s19, 0xb2c00
	s_add_u32 s14, s4, s18
	s_addc_u32 s15, s5, 0
	s_lshl_b32 s19, s19, 3
	s_add_u32 s16, s6, s19
	s_addc_u32 s17, s7, 0
	global_load_dwordx4 v[202:205], v219, s[16:17]
	s_add_i32 m0, s58, 0x0
	s_nop 0
	global_load_lds_dwordx4 v221, s[12:13]
	s_add_i32 m0, s58, 0xc000
	s_nop 0
	global_load_lds_dwordx4 v222, s[14:15]
	s_cmp_lt_u32 s8, s10
	s_cbranch_scc1 .Lat_full_0
	s_cmp_eq_u32 s8, s10
	s_cbranch_scc1 .Lat_last_0

.Lat_nors_f0:
	v_fmamk_f32 v34, v34, 0x3e38aa3b, v234
	v_fmamk_f32 v35, v35, 0x3e38aa3b, v234
	s_waitcnt lgkmcnt(7)
	v_mfma_f32_32x32x16_bf16 v[70:85], v[118:121], v[102:105], 0
	ds_read_b64_tr_b16 v[154:155], v227 offset:0
	ds_read_b64_tr_b16 v[156:157], v227 offset:1024
	v_fmamk_f32 v36, v36, 0x3e38aa3b, v234
	v_fmamk_f32 v37, v37, 0x3e38aa3b, v234
	v_fmamk_f32 v38, v38, 0x3e38aa3b, v234
	v_fmamk_f32 v39, v39, 0x3e38aa3b, v234
	v_fmamk_f32 v40, v40, 0x3e38aa3b, v234
	v_fmamk_f32 v41, v41, 0x3e38aa3b, v234
	v_exp_f32_e32 v34, v34
	v_exp_f32_e32 v35, v35
	v_exp_f32_e32 v36, v36
	v_exp_f32_e32 v37, v37
	v_exp_f32_e32 v38, v38
	v_exp_f32_e32 v39, v39
	s_waitcnt lgkmcnt(8)
	v_mfma_f32_32x32x16_bf16 v[86:101], v[122:125], v[102:105], 0
	ds_read_b64_tr_b16 v[158:159], v228 offset:0
	ds_read_b64_tr_b16 v[160:161], v228 offset:1024
	v_exp_f32_e32 v40, v40
	v_exp_f32_e32 v41, v41
	v_add_f32_e32 v243, v34, v38
	v_add_f32_e32 v244, v35, v39
	v_add_f32_e32 v245, v36, v40
	v_add_f32_e32 v246, v37, v41
	v_cvt_pk_bf16_f32 v34, v34, v35
	v_cvt_pk_bf16_f32 v35, v36, v37
	v_cvt_pk_bf16_f32 v36, v38, v39
	v_cvt_pk_bf16_f32 v37, v40, v41
	v_fmamk_f32 v42, v42, 0x3e38aa3b, v234
	v_fmamk_f32 v43, v43, 0x3e38aa3b, v234
	s_waitcnt lgkmcnt(9)
	v_mfma_f32_32x32x16_bf16 v[70:85], v[126:129], v[106:109], v[70:85]
	ds_read_b64_tr_b16 v[162:163], v227 offset:2048
	ds_read_b64_tr_b16 v[164:165], v227 offset:3072
	v_fmamk_f32 v44, v44, 0x3e38aa3b, v234
	v_fmamk_f32 v45, v45, 0x3e38aa3b, v234
	v_fmamk_f32 v46, v46, 0x3e38aa3b, v234
	v_fmamk_f32 v47, v47, 0x3e38aa3b, v234
	v_fmamk_f32 v48, v48, 0x3e38aa3b, v234
	v_fmamk_f32 v49, v49, 0x3e38aa3b, v234
	v_exp_f32_e32 v42, v42
	v_exp_f32_e32 v43, v43
	v_exp_f32_e32 v44, v44
	v_exp_f32_e32 v45, v45
	v_exp_f32_e32 v46, v46
	v_exp_f32_e32 v47, v47
	s_waitcnt lgkmcnt(10)
	v_mfma_f32_32x32x16_bf16 v[86:101], v[130:133], v[106:109], v[86:101]
	ds_read_b64_tr_b16 v[166:167], v228 offset:2048
	ds_read_b64_tr_b16 v[168:169], v228 offset:3072
	v_exp_f32_e32 v48, v48
	v_exp_f32_e32 v49, v49
	v_add_f32_e32 v243, v243, v42
	v_add_f32_e32 v244, v244, v43
	v_add_f32_e32 v245, v245, v44
	v_add_f32_e32 v246, v246, v45
	v_add_f32_e32 v243, v243, v46
	v_add_f32_e32 v244, v244, v47
	v_add_f32_e32 v245, v245, v48
	v_add_f32_e32 v246, v246, v49
	v_cvt_pk_bf16_f32 v42, v42, v43
	v_cvt_pk_bf16_f32 v43, v44, v45
	s_waitcnt lgkmcnt(11)
	v_mfma_f32_32x32x16_bf16 v[70:85], v[134:137], v[110:113], v[70:85]
	ds_read_b64_tr_b16 v[170:171], v227 offset:4096
	ds_read_b64_tr_b16 v[172:173], v227 offset:5120
	v_cvt_pk_bf16_f32 v44, v46, v47
	v_cvt_pk_bf16_f32 v45, v48, v49
	v_fmamk_f32 v50, v50, 0x3e38aa3b, v234
	v_fmamk_f32 v51, v51, 0x3e38aa3b, v234
	v_fmamk_f32 v52, v52, 0x3e38aa3b, v234
	v_fmamk_f32 v53, v53, 0x3e38aa3b, v234
	v_fmamk_f32 v54, v54, 0x3e38aa3b, v234
	v_fmamk_f32 v55, v55, 0x3e38aa3b, v234
	v_fmamk_f32 v56, v56, 0x3e38aa3b, v234
	v_fmamk_f32 v57, v57, 0x3e38aa3b, v234
	v_exp_f32_e32 v50, v50
	v_exp_f32_e32 v51, v51
	s_waitcnt lgkmcnt(12)
	v_mfma_f32_32x32x16_bf16 v[86:101], v[138:141], v[110:113], v[86:101]
	ds_read_b64_tr_b16 v[174:175], v228 offset:4096
	ds_read_b64_tr_b16 v[176:177], v228 offset:5120
	v_exp_f32_e32 v52, v52
	v_exp_f32_e32 v53, v53
	v_exp_f32_e32 v54, v54
	v_exp_f32_e32 v55, v55
	v_exp_f32_e32 v56, v56
	v_exp_f32_e32 v57, v57
	v_add_f32_e32 v243, v243, v50
	v_add_f32_e32 v244, v244, v51
	v_add_f32_e32 v245, v245, v52
	v_add_f32_e32 v246, v246, v53
	v_add_f32_e32 v243, v243, v54
	v_add_f32_e32 v244, v244, v55
	s_waitcnt lgkmcnt(13)
	v_mfma_f32_32x32x16_bf16 v[70:85], v[142:145], v[114:117], v[70:85]
	ds_read_b64_tr_b16 v[178:179], v227 offset:6144
	ds_read_b64_tr_b16 v[180:181], v227 offset:7168
	v_add_f32_e32 v245, v245, v56
	v_add_f32_e32 v246, v246, v57
	v_cvt_pk_bf16_f32 v50, v50, v51
	v_cvt_pk_bf16_f32 v51, v52, v53
	v_cvt_pk_bf16_f32 v52, v54, v55
	v_cvt_pk_bf16_f32 v53, v56, v57
	v_fmamk_f32 v58, v58, 0x3e38aa3b, v234
	v_fmamk_f32 v59, v59, 0x3e38aa3b, v234
	v_fmamk_f32 v60, v60, 0x3e38aa3b, v234
	v_fmamk_f32 v61, v61, 0x3e38aa3b, v234
	v_fmamk_f32 v62, v62, 0x3e38aa3b, v234
	v_fmamk_f32 v63, v63, 0x3e38aa3b, v234
	s_waitcnt lgkmcnt(14)
	v_mfma_f32_32x32x16_bf16 v[86:101], v[146:149], v[114:117], v[86:101]
	ds_read_b64_tr_b16 v[182:183], v228 offset:6144
	ds_read_b64_tr_b16 v[184:185], v228 offset:7168
	s_waitcnt lgkmcnt(14)
	v_fmamk_f32 v64, v64, 0x3e38aa3b, v234
	v_fmamk_f32 v65, v65, 0x3e38aa3b, v234
	v_exp_f32_e32 v58, v58
	v_exp_f32_e32 v59, v59
	v_exp_f32_e32 v60, v60
	v_exp_f32_e32 v61, v61
	v_exp_f32_e32 v62, v62
	v_exp_f32_e32 v63, v63
	v_exp_f32_e32 v64, v64
	v_exp_f32_e32 v65, v65
	v_add_f32_e32 v243, v243, v58
	v_add_f32_e32 v244, v244, v59
	v_add_f32_e32 v245, v245, v60
	v_add_f32_e32 v246, v246, v61
	s_waitcnt lgkmcnt(14)
	v_mfma_f32_32x32x16_bf16 v[0:15], v[154:157], v[34:37], v[0:15]
	ds_read_b128 v[118:121], v223 offset:16384
	v_add_f32_e32 v243, v243, v62
	v_add_f32_e32 v244, v244, v63
	v_add_f32_e32 v245, v245, v64
	v_add_f32_e32 v246, v246, v65
	v_cvt_pk_bf16_f32 v58, v58, v59
	v_cvt_pk_bf16_f32 v59, v60, v61
	v_cvt_pk_bf16_f32 v60, v62, v63
	v_cvt_pk_bf16_f32 v61, v64, v65
	v_add_f32_e32 v243, v243, v244
	v_add_f32_e32 v245, v245, v246
	v_add_f32_e32 v243, v243, v245
	v_fma_f32 v231, v231, v232, v243
	s_waitcnt lgkmcnt(13)
	v_mfma_f32_32x32x16_bf16 v[16:31], v[158:161], v[34:37], v[16:31]
	ds_read_b128 v[122:125], v223 offset:20480
	v_lshrrev_b32_e32 v249, v229, v200
	v_lshrrev_b32_e32 v250, v229, v201
	v_bfe_i32 v235, v249, 0, 1
	v_bfe_i32 v236, v250, 0, 1
	v_bfe_i32 v237, v249, 1, 1
	v_bfe_i32 v238, v250, 1, 1
	v_bfe_i32 v239, v249, 2, 1
	v_bfe_i32 v240, v250, 2, 1
	v_bfe_i32 v241, v249, 3, 1
	v_bfe_i32 v242, v250, 3, 1
	v_bitop3_b32 v70, v70, s33, v235 bitop3:0xe4
	s_waitcnt lgkmcnt(12)
	v_mfma_f32_32x32x16_bf16 v[0:15], v[162:165], v[42:45], v[0:15]
	ds_read_b128 v[126:129], v224 offset:16384
	v_bitop3_b32 v86, v86, s33, v236 bitop3:0xe4
	v_bitop3_b32 v71, v71, s33, v237 bitop3:0xe4
	v_bitop3_b32 v87, v87, s33, v238 bitop3:0xe4
	v_bitop3_b32 v72, v72, s33, v239 bitop3:0xe4
	v_bitop3_b32 v88, v88, s33, v240 bitop3:0xe4
	v_bitop3_b32 v73, v73, s33, v241 bitop3:0xe4
	v_bitop3_b32 v89, v89, s33, v242 bitop3:0xe4
	v_max3_f32 v247, v70, s33, v86
	v_max3_f32 v248, v71, s33, v87
	v_max3_f32 v247, v247, v72, v88
	v_max3_f32 v248, v248, v73, v89
	v_bfe_i32 v235, v249, 8, 1
	s_waitcnt lgkmcnt(11)
	v_mfma_f32_32x32x16_bf16 v[16:31], v[166:169], v[42:45], v[16:31]
	ds_read_b128 v[130:133], v224 offset:20480
	v_bfe_i32 v236, v250, 8, 1
	v_bfe_i32 v237, v249, 9, 1
	v_bfe_i32 v238, v250, 9, 1
	v_bfe_i32 v239, v249, 10, 1
	v_bfe_i32 v240, v250, 10, 1
	v_bfe_i32 v241, v249, 11, 1
	v_bfe_i32 v242, v250, 11, 1
	v_bitop3_b32 v74, v74, s33, v235 bitop3:0xe4
	v_bitop3_b32 v90, v90, s33, v236 bitop3:0xe4
	v_bitop3_b32 v75, v75, s33, v237 bitop3:0xe4
	v_bitop3_b32 v91, v91, s33, v238 bitop3:0xe4
	v_bitop3_b32 v76, v76, s33, v239 bitop3:0xe4
	s_waitcnt lgkmcnt(10)
	v_mfma_f32_32x32x16_bf16 v[0:15], v[170:173], v[50:53], v[0:15]
	ds_read_b128 v[134:137], v225 offset:16384
	v_bitop3_b32 v92, v92, s33, v240 bitop3:0xe4
	v_bitop3_b32 v77, v77, s33, v241 bitop3:0xe4
	v_bitop3_b32 v93, v93, s33, v242 bitop3:0xe4
	v_max3_f32 v247, v247, v74, v90
	v_max3_f32 v248, v248, v75, v91
	v_max3_f32 v247, v247, v76, v92
	v_max3_f32 v248, v248, v77, v93
	v_bfe_i32 v235, v249, 16, 1
	v_bfe_i32 v236, v250, 16, 1
	v_bfe_i32 v237, v249, 17, 1
	v_bfe_i32 v238, v250, 17, 1
	v_bfe_i32 v239, v249, 18, 1
	s_waitcnt lgkmcnt(9)
	v_mfma_f32_32x32x16_bf16 v[16:31], v[174:177], v[50:53], v[16:31]
	ds_read_b128 v[138:141], v225 offset:20480
	v_bfe_i32 v240, v250, 18, 1
	v_bfe_i32 v241, v249, 19, 1
	v_bfe_i32 v242, v250, 19, 1
	v_bitop3_b32 v78, v78, s33, v235 bitop3:0xe4
	v_bitop3_b32 v94, v94, s33, v236 bitop3:0xe4
	v_bitop3_b32 v79, v79, s33, v237 bitop3:0xe4
	v_bitop3_b32 v95, v95, s33, v238 bitop3:0xe4
	v_bitop3_b32 v80, v80, s33, v239 bitop3:0xe4
	v_bitop3_b32 v96, v96, s33, v240 bitop3:0xe4
	v_bitop3_b32 v81, v81, s33, v241 bitop3:0xe4
	v_bitop3_b32 v97, v97, s33, v242 bitop3:0xe4
	v_max3_f32 v247, v247, v78, v94
	s_waitcnt lgkmcnt(8)
	v_mfma_f32_32x32x16_bf16 v[0:15], v[178:181], v[58:61], v[0:15]
	ds_read_b128 v[142:145], v226 offset:16384
	v_max3_f32 v248, v248, v79, v95
	v_max3_f32 v247, v247, v80, v96
	v_max3_f32 v248, v248, v81, v97
	v_bfe_i32 v235, v249, 24, 1
	v_bfe_i32 v236, v250, 24, 1
	v_bfe_i32 v237, v249, 25, 1
	v_bfe_i32 v238, v250, 25, 1
	v_bfe_i32 v239, v249, 26, 1
	v_bfe_i32 v240, v250, 26, 1
	v_bfe_i32 v241, v249, 27, 1
	v_bfe_i32 v242, v250, 27, 1
	v_bitop3_b32 v82, v82, s33, v235 bitop3:0xe4
	s_waitcnt lgkmcnt(7)
	v_mfma_f32_32x32x16_bf16 v[16:31], v[182:185], v[58:61], v[16:31]
	ds_read_b128 v[146:149], v226 offset:20480
	v_bitop3_b32 v98, v98, s33, v236 bitop3:0xe4
	v_bitop3_b32 v83, v83, s33, v237 bitop3:0xe4
	v_bitop3_b32 v99, v99, s33, v238 bitop3:0xe4
	v_bitop3_b32 v84, v84, s33, v239 bitop3:0xe4
	v_bitop3_b32 v100, v100, s33, v240 bitop3:0xe4
	v_bitop3_b32 v85, v85, s33, v241 bitop3:0xe4
	v_bitop3_b32 v101, v101, s33, v242 bitop3:0xe4
	v_max3_f32 v247, v247, v82, v98
	v_max3_f32 v248, v248, v83, v99
	v_max3_f32 v247, v247, v84, v100
	v_max3_f32 v248, v248, v85, v101
	v_max_f32_e32 v247, v247, v248
	v_mov_b32_e32 v248, v247
	s_nop 1
	v_permlane32_swap_b32_e32 v247, v248
	v_max3_f32 v247, v230, v247, v248
	v_cmp_neq_f32_e32 vcc, s33, v247
	s_nop 1
	v_cndmask_b32_e32 v248, 0, v247, vcc
	v_sub_f32_e32 v33, v230, v248
	v_mul_f32_e32 v33, 0x3e38aa3b, v33
	v_exp_f32_e32 v232, v33
	v_mul_f32_e32 v234, 0xbe38aa3b, v248
	v_mov_b32_e32 v230, v247
	s_waitcnt vmcnt(3)
	s_barrier
	s_add_u32 s8, s8, 1
	s_cmp_lt_u32 s8, s9
	s_cbranch_scc1 .Lat_loop_1
	s_branch .Lat_epilogue

.Lat_loop_1:
	s_add_u32 s18, s8, 4
	s_min_u32 s18, s18, s11
	s_mul_i32 s18, s18, 0xb2c00
	s_add_u32 s12, s4, s18
	s_addc_u32 s13, s5, 0
	s_add_u32 s19, s8, 2
	s_min_u32 s19, s19, s11
	s_mul_i32 s18, s19, 0xb2c00
	s_add_u32 s14, s4, s18
	s_addc_u32 s15, s5, 0
	s_add_i32 m0, s58, 0x2000
	s_nop 0
	global_load_lds_dwordx4 v221, s[12:13]
	s_add_i32 m0, s58, 0xe000
	s_nop 0
	global_load_lds_dwordx4 v222, s[14:15]
	s_cmp_lt_u32 s8, s10
	s_cbranch_scc1 .Lat_full_1
	s_cmp_eq_u32 s8, s10
	s_cbranch_scc1 .Lat_last_1
.Lat_idle_1:
	s_waitcnt vmcnt(2)
	s_barrier
	s_add_u32 s8, s8, 1
	s_cmp_lt_u32 s8, s9
	s_cbranch_scc1 .Lat_loop_2
	s_branch .Lat_epilogue

.Lat_nors_f1:
	v_fmamk_f32 v70, v70, 0x3e38aa3b, v234
	v_fmamk_f32 v71, v71, 0x3e38aa3b, v234
	s_waitcnt lgkmcnt(7)
	v_mfma_f32_32x32x16_bf16 v[34:49], v[118:121], v[102:105], 0
	ds_read_b64_tr_b16 v[154:155], v227 offset:8192
	ds_read_b64_tr_b16 v[156:157], v227 offset:9216
	v_fmamk_f32 v72, v72, 0x3e38aa3b, v234
	v_fmamk_f32 v73, v73, 0x3e38aa3b, v234
	v_fmamk_f32 v74, v74, 0x3e38aa3b, v234
	v_fmamk_f32 v75, v75, 0x3e38aa3b, v234
	v_fmamk_f32 v76, v76, 0x3e38aa3b, v234
	v_fmamk_f32 v77, v77, 0x3e38aa3b, v234
	v_exp_f32_e32 v70, v70
	v_exp_f32_e32 v71, v71
	v_exp_f32_e32 v72, v72
	v_exp_f32_e32 v73, v73
	v_exp_f32_e32 v74, v74
	v_exp_f32_e32 v75, v75
	s_waitcnt lgkmcnt(8)
	v_mfma_f32_32x32x16_bf16 v[50:65], v[122:125], v[102:105], 0
	ds_read_b64_tr_b16 v[158:159], v228 offset:8192
	ds_read_b64_tr_b16 v[160:161], v228 offset:9216
	v_exp_f32_e32 v76, v76
	v_exp_f32_e32 v77, v77
	v_add_f32_e32 v243, v70, v74
	v_add_f32_e32 v244, v71, v75
	v_add_f32_e32 v245, v72, v76
	v_add_f32_e32 v246, v73, v77
	v_cvt_pk_bf16_f32 v70, v70, v71
	v_cvt_pk_bf16_f32 v71, v72, v73
	v_cvt_pk_bf16_f32 v72, v74, v75
	v_cvt_pk_bf16_f32 v73, v76, v77
	v_fmamk_f32 v78, v78, 0x3e38aa3b, v234
	v_fmamk_f32 v79, v79, 0x3e38aa3b, v234
	s_waitcnt lgkmcnt(9)
	v_mfma_f32_32x32x16_bf16 v[34:49], v[126:129], v[106:109], v[34:49]
	ds_read_b64_tr_b16 v[162:163], v227 offset:10240
	ds_read_b64_tr_b16 v[164:165], v227 offset:11264
	v_fmamk_f32 v80, v80, 0x3e38aa3b, v234
	v_fmamk_f32 v81, v81, 0x3e38aa3b, v234
	v_fmamk_f32 v82, v82, 0x3e38aa3b, v234
	v_fmamk_f32 v83, v83, 0x3e38aa3b, v234
	v_fmamk_f32 v84, v84, 0x3e38aa3b, v234
	v_fmamk_f32 v85, v85, 0x3e38aa3b, v234
	v_exp_f32_e32 v78, v78
	v_exp_f32_e32 v79, v79
	v_exp_f32_e32 v80, v80
	v_exp_f32_e32 v81, v81
	v_exp_f32_e32 v82, v82
	v_exp_f32_e32 v83, v83
	s_waitcnt lgkmcnt(10)
	v_mfma_f32_32x32x16_bf16 v[50:65], v[130:133], v[106:109], v[50:65]
	ds_read_b64_tr_b16 v[166:167], v228 offset:10240
	ds_read_b64_tr_b16 v[168:169], v228 offset:11264
	v_exp_f32_e32 v84, v84
	v_exp_f32_e32 v85, v85
	v_add_f32_e32 v243, v243, v78
	v_add_f32_e32 v244, v244, v79
	v_add_f32_e32 v245, v245, v80
	v_add_f32_e32 v246, v246, v81
	v_add_f32_e32 v243, v243, v82
	v_add_f32_e32 v244, v244, v83
	v_add_f32_e32 v245, v245, v84
	v_add_f32_e32 v246, v246, v85
	v_cvt_pk_bf16_f32 v78, v78, v79
	v_cvt_pk_bf16_f32 v79, v80, v81
	s_waitcnt lgkmcnt(11)
	v_mfma_f32_32x32x16_bf16 v[34:49], v[134:137], v[110:113], v[34:49]
	ds_read_b64_tr_b16 v[170:171], v227 offset:12288
	ds_read_b64_tr_b16 v[172:173], v227 offset:13312
	v_cvt_pk_bf16_f32 v80, v82, v83
	v_cvt_pk_bf16_f32 v81, v84, v85
	v_fmamk_f32 v86, v86, 0x3e38aa3b, v234
	v_fmamk_f32 v87, v87, 0x3e38aa3b, v234
	v_fmamk_f32 v88, v88, 0x3e38aa3b, v234
	v_fmamk_f32 v89, v89, 0x3e38aa3b, v234
	v_fmamk_f32 v90, v90, 0x3e38aa3b, v234
	v_fmamk_f32 v91, v91, 0x3e38aa3b, v234
	v_fmamk_f32 v92, v92, 0x3e38aa3b, v234
	v_fmamk_f32 v93, v93, 0x3e38aa3b, v234
	v_exp_f32_e32 v86, v86
	v_exp_f32_e32 v87, v87
	s_waitcnt lgkmcnt(12)
	v_mfma_f32_32x32x16_bf16 v[50:65], v[138:141], v[110:113], v[50:65]
	ds_read_b64_tr_b16 v[174:175], v228 offset:12288
	ds_read_b64_tr_b16 v[176:177], v228 offset:13312
	v_exp_f32_e32 v88, v88
	v_exp_f32_e32 v89, v89
	v_exp_f32_e32 v90, v90
	v_exp_f32_e32 v91, v91
	v_exp_f32_e32 v92, v92
	v_exp_f32_e32 v93, v93
	v_add_f32_e32 v243, v243, v86
	v_add_f32_e32 v244, v244, v87
	v_add_f32_e32 v245, v245, v88
	v_add_f32_e32 v246, v246, v89
	v_add_f32_e32 v243, v243, v90
	v_add_f32_e32 v244, v244, v91
	s_waitcnt lgkmcnt(13)
	v_mfma_f32_32x32x16_bf16 v[34:49], v[142:145], v[114:117], v[34:49]
	ds_read_b64_tr_b16 v[178:179], v227 offset:14336
	ds_read_b64_tr_b16 v[180:181], v227 offset:15360
	v_add_f32_e32 v245, v245, v92
	v_add_f32_e32 v246, v246, v93
	v_cvt_pk_bf16_f32 v86, v86, v87
	v_cvt_pk_bf16_f32 v87, v88, v89
	v_cvt_pk_bf16_f32 v88, v90, v91
	v_cvt_pk_bf16_f32 v89, v92, v93
	v_fmamk_f32 v94, v94, 0x3e38aa3b, v234
	v_fmamk_f32 v95, v95, 0x3e38aa3b, v234
	v_fmamk_f32 v96, v96, 0x3e38aa3b, v234
	v_fmamk_f32 v97, v97, 0x3e38aa3b, v234
	v_fmamk_f32 v98, v98, 0x3e38aa3b, v234
	v_fmamk_f32 v99, v99, 0x3e38aa3b, v234
	s_waitcnt lgkmcnt(14)
	v_mfma_f32_32x32x16_bf16 v[50:65], v[146:149], v[114:117], v[50:65]
	ds_read_b64_tr_b16 v[182:183], v228 offset:14336
	ds_read_b64_tr_b16 v[184:185], v228 offset:15360
	s_waitcnt lgkmcnt(14)
	v_fmamk_f32 v100, v100, 0x3e38aa3b, v234
	v_fmamk_f32 v101, v101, 0x3e38aa3b, v234
	v_exp_f32_e32 v94, v94
	v_exp_f32_e32 v95, v95
	v_exp_f32_e32 v96, v96
	v_exp_f32_e32 v97, v97
	v_exp_f32_e32 v98, v98
	v_exp_f32_e32 v99, v99
	v_exp_f32_e32 v100, v100
	v_exp_f32_e32 v101, v101
	v_add_f32_e32 v243, v243, v94
	v_add_f32_e32 v244, v244, v95
	v_add_f32_e32 v245, v245, v96
	v_add_f32_e32 v246, v246, v97
	s_waitcnt lgkmcnt(14)
	v_mfma_f32_32x32x16_bf16 v[0:15], v[154:157], v[70:73], v[0:15]
	ds_read_b128 v[118:121], v223 offset:24576
	v_add_f32_e32 v243, v243, v98
	v_add_f32_e32 v244, v244, v99
	v_add_f32_e32 v245, v245, v100
	v_add_f32_e32 v246, v246, v101
	v_cvt_pk_bf16_f32 v94, v94, v95
	v_cvt_pk_bf16_f32 v95, v96, v97
	v_cvt_pk_bf16_f32 v96, v98, v99
	v_cvt_pk_bf16_f32 v97, v100, v101
	v_add_f32_e32 v243, v243, v244
	v_add_f32_e32 v245, v245, v246
	v_add_f32_e32 v243, v243, v245
	v_fma_f32 v231, v231, v232, v243
	s_waitcnt lgkmcnt(13)
	v_mfma_f32_32x32x16_bf16 v[16:31], v[158:161], v[70:73], v[16:31]
	ds_read_b128 v[122:125], v223 offset:28672
	s_waitcnt vmcnt(4)
	v_lshrrev_b32_e32 v249, v229, v202
	v_lshrrev_b32_e32 v250, v229, v203
	v_bfe_i32 v235, v249, 0, 1
	v_bfe_i32 v236, v250, 0, 1
	v_bfe_i32 v237, v249, 1, 1
	v_bfe_i32 v238, v250, 1, 1
	v_bfe_i32 v239, v249, 2, 1
	v_bfe_i32 v240, v250, 2, 1
	v_bfe_i32 v241, v249, 3, 1
	v_bfe_i32 v242, v250, 3, 1
	v_bitop3_b32 v34, v34, s33, v235 bitop3:0xe4
	s_waitcnt lgkmcnt(12)
	v_mfma_f32_32x32x16_bf16 v[0:15], v[162:165], v[78:81], v[0:15]
	ds_read_b128 v[126:129], v224 offset:24576
	v_bitop3_b32 v50, v50, s33, v236 bitop3:0xe4
	v_bitop3_b32 v35, v35, s33, v237 bitop3:0xe4
	v_bitop3_b32 v51, v51, s33, v238 bitop3:0xe4
	v_bitop3_b32 v36, v36, s33, v239 bitop3:0xe4
	v_bitop3_b32 v52, v52, s33, v240 bitop3:0xe4
	v_bitop3_b32 v37, v37, s33, v241 bitop3:0xe4
	v_bitop3_b32 v53, v53, s33, v242 bitop3:0xe4
	v_max3_f32 v247, v34, s33, v50
	v_max3_f32 v248, v35, s33, v51
	v_max3_f32 v247, v247, v36, v52
	v_max3_f32 v248, v248, v37, v53
	v_bfe_i32 v235, v249, 8, 1
	s_waitcnt lgkmcnt(11)
	v_mfma_f32_32x32x16_bf16 v[16:31], v[166:169], v[78:81], v[16:31]
	ds_read_b128 v[130:133], v224 offset:28672
	v_bfe_i32 v236, v250, 8, 1
	v_bfe_i32 v237, v249, 9, 1
	v_bfe_i32 v238, v250, 9, 1
	v_bfe_i32 v239, v249, 10, 1
	v_bfe_i32 v240, v250, 10, 1
	v_bfe_i32 v241, v249, 11, 1
	v_bfe_i32 v242, v250, 11, 1
	v_bitop3_b32 v38, v38, s33, v235 bitop3:0xe4
	v_bitop3_b32 v54, v54, s33, v236 bitop3:0xe4
	v_bitop3_b32 v39, v39, s33, v237 bitop3:0xe4
	v_bitop3_b32 v55, v55, s33, v238 bitop3:0xe4
	v_bitop3_b32 v40, v40, s33, v239 bitop3:0xe4
	s_waitcnt lgkmcnt(10)
	v_mfma_f32_32x32x16_bf16 v[0:15], v[170:173], v[86:89], v[0:15]
	ds_read_b128 v[134:137], v225 offset:24576
	v_bitop3_b32 v56, v56, s33, v240 bitop3:0xe4
	v_bitop3_b32 v41, v41, s33, v241 bitop3:0xe4
	v_bitop3_b32 v57, v57, s33, v242 bitop3:0xe4
	v_max3_f32 v247, v247, v38, v54
	v_max3_f32 v248, v248, v39, v55
	v_max3_f32 v247, v247, v40, v56
	v_max3_f32 v248, v248, v41, v57
	v_bfe_i32 v235, v249, 16, 1
	v_bfe_i32 v236, v250, 16, 1
	v_bfe_i32 v237, v249, 17, 1
	v_bfe_i32 v238, v250, 17, 1
	v_bfe_i32 v239, v249, 18, 1
	s_waitcnt lgkmcnt(9)
	v_mfma_f32_32x32x16_bf16 v[16:31], v[174:177], v[86:89], v[16:31]
	ds_read_b128 v[138:141], v225 offset:28672
	v_bfe_i32 v240, v250, 18, 1
	v_bfe_i32 v241, v249, 19, 1
	v_bfe_i32 v242, v250, 19, 1
	v_bitop3_b32 v42, v42, s33, v235 bitop3:0xe4
	v_bitop3_b32 v58, v58, s33, v236 bitop3:0xe4
	v_bitop3_b32 v43, v43, s33, v237 bitop3:0xe4
	v_bitop3_b32 v59, v59, s33, v238 bitop3:0xe4
	v_bitop3_b32 v44, v44, s33, v239 bitop3:0xe4
	v_bitop3_b32 v60, v60, s33, v240 bitop3:0xe4
	v_bitop3_b32 v45, v45, s33, v241 bitop3:0xe4
	v_bitop3_b32 v61, v61, s33, v242 bitop3:0xe4
	v_max3_f32 v247, v247, v42, v58
	s_waitcnt lgkmcnt(8)
	v_mfma_f32_32x32x16_bf16 v[0:15], v[178:181], v[94:97], v[0:15]
	ds_read_b128 v[142:145], v226 offset:24576
	v_max3_f32 v248, v248, v43, v59
	v_max3_f32 v247, v247, v44, v60
	v_max3_f32 v248, v248, v45, v61
	v_bfe_i32 v235, v249, 24, 1
	v_bfe_i32 v236, v250, 24, 1
	v_bfe_i32 v237, v249, 25, 1
	v_bfe_i32 v238, v250, 25, 1
	v_bfe_i32 v239, v249, 26, 1
	v_bfe_i32 v240, v250, 26, 1
	v_bfe_i32 v241, v249, 27, 1
	v_bfe_i32 v242, v250, 27, 1
	v_bitop3_b32 v46, v46, s33, v235 bitop3:0xe4
	s_waitcnt lgkmcnt(7)
	v_mfma_f32_32x32x16_bf16 v[16:31], v[182:185], v[94:97], v[16:31]
	ds_read_b128 v[146:149], v226 offset:28672
	v_bitop3_b32 v62, v62, s33, v236 bitop3:0xe4
	v_bitop3_b32 v47, v47, s33, v237 bitop3:0xe4
	v_bitop3_b32 v63, v63, s33, v238 bitop3:0xe4
	v_bitop3_b32 v48, v48, s33, v239 bitop3:0xe4
	v_bitop3_b32 v64, v64, s33, v240 bitop3:0xe4
	v_bitop3_b32 v49, v49, s33, v241 bitop3:0xe4
	v_bitop3_b32 v65, v65, s33, v242 bitop3:0xe4
	v_max3_f32 v247, v247, v46, v62
	v_max3_f32 v248, v248, v47, v63
	v_max3_f32 v247, v247, v48, v64
	v_max3_f32 v248, v248, v49, v65
	v_max_f32_e32 v247, v247, v248
	v_mov_b32_e32 v248, v247
	s_nop 1
	v_permlane32_swap_b32_e32 v247, v248
	v_max3_f32 v247, v230, v247, v248
	v_cmp_neq_f32_e32 vcc, s33, v247
	s_nop 1
	v_cndmask_b32_e32 v248, 0, v247, vcc
	v_sub_f32_e32 v33, v230, v248
	v_mul_f32_e32 v33, 0x3e38aa3b, v33
	v_exp_f32_e32 v232, v33
	v_mul_f32_e32 v234, 0xbe38aa3b, v248
	v_mov_b32_e32 v230, v247
	s_waitcnt vmcnt(2)
	s_barrier
	s_add_u32 s8, s8, 1
	s_cmp_lt_u32 s8, s9
	s_cbranch_scc1 .Lat_loop_2
	s_branch .Lat_epilogue

.Lat_nors_l1:
	v_fmamk_f32 v70, v70, 0x3e38aa3b, v234
	v_fmamk_f32 v71, v71, 0x3e38aa3b, v234
	v_fmamk_f32 v72, v72, 0x3e38aa3b, v234
	ds_read_b64_tr_b16 v[168:169], v228 offset:11264
	s_waitcnt lgkmcnt(14)
	v_fmamk_f32 v73, v73, 0x3e38aa3b, v234
	v_fmamk_f32 v74, v74, 0x3e38aa3b, v234
	v_fmamk_f32 v75, v75, 0x3e38aa3b, v234
	ds_read_b64_tr_b16 v[170:171], v227 offset:12288
	s_waitcnt lgkmcnt(14)
	v_fmamk_f32 v76, v76, 0x3e38aa3b, v234
	v_fmamk_f32 v77, v77, 0x3e38aa3b, v234
	v_exp_f32_e32 v70, v70
	ds_read_b64_tr_b16 v[172:173], v227 offset:13312
	s_waitcnt lgkmcnt(14)
	v_exp_f32_e32 v71, v71
	v_exp_f32_e32 v72, v72
	v_exp_f32_e32 v73, v73
	ds_read_b64_tr_b16 v[174:175], v228 offset:12288
	s_waitcnt lgkmcnt(14)
	v_exp_f32_e32 v74, v74
	v_exp_f32_e32 v75, v75
	v_exp_f32_e32 v76, v76
	ds_read_b64_tr_b16 v[176:177], v228 offset:13312
	s_waitcnt lgkmcnt(14)
	v_exp_f32_e32 v77, v77
	v_add_f32_e32 v243, v70, v74
	v_add_f32_e32 v244, v71, v75
	ds_read_b64_tr_b16 v[178:179], v227 offset:14336
	s_waitcnt lgkmcnt(14)
	v_add_f32_e32 v245, v72, v76
	v_add_f32_e32 v246, v73, v77
	v_cvt_pk_bf16_f32 v70, v70, v71
	ds_read_b64_tr_b16 v[180:181], v227 offset:15360
	s_waitcnt lgkmcnt(14)
	v_cvt_pk_bf16_f32 v71, v72, v73
	v_cvt_pk_bf16_f32 v72, v74, v75
	v_cvt_pk_bf16_f32 v73, v76, v77
	ds_read_b64_tr_b16 v[182:183], v228 offset:14336
	s_waitcnt lgkmcnt(14)
	s_waitcnt lgkmcnt(13)
	v_mfma_f32_32x32x16_bf16 v[0:15], v[154:157], v[70:73], v[0:15]
	s_waitcnt lgkmcnt(11)
	v_mfma_f32_32x32x16_bf16 v[16:31], v[158:161], v[70:73], v[16:31]
	v_fmamk_f32 v78, v78, 0x3e38aa3b, v234
	v_fmamk_f32 v79, v79, 0x3e38aa3b, v234
	v_fmamk_f32 v80, v80, 0x3e38aa3b, v234
	ds_read_b64_tr_b16 v[184:185], v228 offset:15360
	v_fmamk_f32 v81, v81, 0x3e38aa3b, v234
	v_fmamk_f32 v82, v82, 0x3e38aa3b, v234
	v_fmamk_f32 v83, v83, 0x3e38aa3b, v234
	v_fmamk_f32 v84, v84, 0x3e38aa3b, v234
	v_fmamk_f32 v85, v85, 0x3e38aa3b, v234
	v_exp_f32_e32 v78, v78
	v_exp_f32_e32 v79, v79
	v_exp_f32_e32 v80, v80
	v_exp_f32_e32 v81, v81
	v_exp_f32_e32 v82, v82
	v_exp_f32_e32 v83, v83
	v_exp_f32_e32 v84, v84
	v_exp_f32_e32 v85, v85
	v_add_f32_e32 v243, v243, v78
	v_add_f32_e32 v244, v244, v79
	v_add_f32_e32 v245, v245, v80
	v_add_f32_e32 v246, v246, v81
	v_add_f32_e32 v243, v243, v82
	v_add_f32_e32 v244, v244, v83
	v_add_f32_e32 v245, v245, v84
	v_add_f32_e32 v246, v246, v85
	v_cvt_pk_bf16_f32 v78, v78, v79
	v_cvt_pk_bf16_f32 v79, v80, v81
	v_cvt_pk_bf16_f32 v80, v82, v83
	v_cvt_pk_bf16_f32 v81, v84, v85
	s_waitcnt lgkmcnt(10)
	v_mfma_f32_32x32x16_bf16 v[0:15], v[162:165], v[78:81], v[0:15]
	s_waitcnt lgkmcnt(8)
	v_mfma_f32_32x32x16_bf16 v[16:31], v[166:169], v[78:81], v[16:31]
	v_fmamk_f32 v86, v86, 0x3e38aa3b, v234
	v_fmamk_f32 v87, v87, 0x3e38aa3b, v234
	v_fmamk_f32 v88, v88, 0x3e38aa3b, v234
	v_fmamk_f32 v89, v89, 0x3e38aa3b, v234
	v_fmamk_f32 v90, v90, 0x3e38aa3b, v234
	v_fmamk_f32 v91, v91, 0x3e38aa3b, v234
	v_fmamk_f32 v92, v92, 0x3e38aa3b, v234
	v_fmamk_f32 v93, v93, 0x3e38aa3b, v234
	v_exp_f32_e32 v86, v86
	v_exp_f32_e32 v87, v87
	v_exp_f32_e32 v88, v88
	v_exp_f32_e32 v89, v89
	v_exp_f32_e32 v90, v90
	v_exp_f32_e32 v91, v91
	v_exp_f32_e32 v92, v92
	v_exp_f32_e32 v93, v93
	v_add_f32_e32 v243, v243, v86
	v_add_f32_e32 v244, v244, v87
	v_add_f32_e32 v245, v245, v88
	v_add_f32_e32 v246, v246, v89
	v_add_f32_e32 v243, v243, v90
	v_add_f32_e32 v244, v244, v91
	v_add_f32_e32 v245, v245, v92
	v_add_f32_e32 v246, v246, v93
	v_cvt_pk_bf16_f32 v86, v86, v87
	v_cvt_pk_bf16_f32 v87, v88, v89
	v_cvt_pk_bf16_f32 v88, v90, v91
	v_cvt_pk_bf16_f32 v89, v92, v93
	s_waitcnt lgkmcnt(6)
	v_mfma_f32_32x32x16_bf16 v[0:15], v[170:173], v[86:89], v[0:15]
	s_waitcnt lgkmcnt(4)
	v_mfma_f32_32x32x16_bf16 v[16:31], v[174:177], v[86:89], v[16:31]
	v_fmamk_f32 v94, v94, 0x3e38aa3b, v234
	v_fmamk_f32 v95, v95, 0x3e38aa3b, v234
	v_fmamk_f32 v96, v96, 0x3e38aa3b, v234
	v_fmamk_f32 v97, v97, 0x3e38aa3b, v234
	v_fmamk_f32 v98, v98, 0x3e38aa3b, v234
	v_fmamk_f32 v99, v99, 0x3e38aa3b, v234
	v_fmamk_f32 v100, v100, 0x3e38aa3b, v234
	v_fmamk_f32 v101, v101, 0x3e38aa3b, v234
	v_exp_f32_e32 v94, v94
	v_exp_f32_e32 v95, v95
	v_exp_f32_e32 v96, v96
	v_exp_f32_e32 v97, v97
	v_exp_f32_e32 v98, v98
	v_exp_f32_e32 v99, v99
	v_exp_f32_e32 v100, v100
	v_exp_f32_e32 v101, v101
	v_add_f32_e32 v243, v243, v94
	v_add_f32_e32 v244, v244, v95
	v_add_f32_e32 v245, v245, v96
	v_add_f32_e32 v246, v246, v97
	v_add_f32_e32 v243, v243, v98
	v_add_f32_e32 v244, v244, v99
	v_add_f32_e32 v245, v245, v100
	v_add_f32_e32 v246, v246, v101
	v_cvt_pk_bf16_f32 v94, v94, v95
	v_cvt_pk_bf16_f32 v95, v96, v97
	v_cvt_pk_bf16_f32 v96, v98, v99
	v_cvt_pk_bf16_f32 v97, v100, v101
	v_add_f32_e32 v243, v243, v244
	v_add_f32_e32 v245, v245, v246
	v_add_f32_e32 v243, v243, v245
	v_fma_f32 v231, v231, v232, v243
	s_waitcnt lgkmcnt(2)
	v_mfma_f32_32x32x16_bf16 v[0:15], v[178:181], v[94:97], v[0:15]
	s_waitcnt lgkmcnt(0)
	v_mfma_f32_32x32x16_bf16 v[16:31], v[182:185], v[94:97], v[16:31]
	s_waitcnt vmcnt(2)
	s_barrier
	s_add_u32 s8, s8, 1
	s_cmp_lt_u32 s8, s9
	s_cbranch_scc1 .Lat_loop_2
	s_branch .Lat_epilogue
.Lat_loop_2:
	s_add_u32 s18, s8, 4
	s_min_u32 s18, s18, s11
	s_mul_i32 s18, s18, 0xb2c00
	s_add_u32 s12, s4, s18
	s_addc_u32 s13, s5, 0
	s_add_u32 s19, s8, 2
	s_min_u32 s19, s19, s11
	s_mul_i32 s18, s19, 0xb2c00
	s_add_u32 s14, s4, s18
	s_addc_u32 s15, s5, 0
	s_lshl_b32 s19, s19, 3
	s_add_u32 s16, s6, s19
	s_addc_u32 s17, s7, 0
	global_load_dwordx4 v[198:201], v219, s[16:17]
	s_add_i32 m0, s58, 0x4000
	s_nop 0
	global_load_lds_dwordx4 v221, s[12:13]
	s_add_i32 m0, s58, 0x8000
	s_nop 0
	global_load_lds_dwordx4 v222, s[14:15]
	s_cmp_lt_u32 s8, s10
	s_cbranch_scc1 .Lat_full_2
	s_cmp_eq_u32 s8, s10
	s_cbranch_scc1 .Lat_last_2

.Lat_nors_f2:
	v_fmamk_f32 v34, v34, 0x3e38aa3b, v234
	v_fmamk_f32 v35, v35, 0x3e38aa3b, v234
	s_waitcnt lgkmcnt(7)
	v_mfma_f32_32x32x16_bf16 v[70:85], v[118:121], v[102:105], 0
	ds_read_b64_tr_b16 v[154:155], v227 offset:16384
	ds_read_b64_tr_b16 v[156:157], v227 offset:17408
	v_fmamk_f32 v36, v36, 0x3e38aa3b, v234
	v_fmamk_f32 v37, v37, 0x3e38aa3b, v234
	v_fmamk_f32 v38, v38, 0x3e38aa3b, v234
	v_fmamk_f32 v39, v39, 0x3e38aa3b, v234
	v_fmamk_f32 v40, v40, 0x3e38aa3b, v234
	v_fmamk_f32 v41, v41, 0x3e38aa3b, v234
	v_exp_f32_e32 v34, v34
	v_exp_f32_e32 v35, v35
	v_exp_f32_e32 v36, v36
	v_exp_f32_e32 v37, v37
	v_exp_f32_e32 v38, v38
	v_exp_f32_e32 v39, v39
	s_waitcnt lgkmcnt(8)
	v_mfma_f32_32x32x16_bf16 v[86:101], v[122:125], v[102:105], 0
	ds_read_b64_tr_b16 v[158:159], v228 offset:16384
	ds_read_b64_tr_b16 v[160:161], v228 offset:17408
	v_exp_f32_e32 v40, v40
	v_exp_f32_e32 v41, v41
	v_add_f32_e32 v243, v34, v38
	v_add_f32_e32 v244, v35, v39
	v_add_f32_e32 v245, v36, v40
	v_add_f32_e32 v246, v37, v41
	v_cvt_pk_bf16_f32 v34, v34, v35
	v_cvt_pk_bf16_f32 v35, v36, v37
	v_cvt_pk_bf16_f32 v36, v38, v39
	v_cvt_pk_bf16_f32 v37, v40, v41
	v_fmamk_f32 v42, v42, 0x3e38aa3b, v234
	v_fmamk_f32 v43, v43, 0x3e38aa3b, v234
	s_waitcnt lgkmcnt(9)
	v_mfma_f32_32x32x16_bf16 v[70:85], v[126:129], v[106:109], v[70:85]
	ds_read_b64_tr_b16 v[162:163], v227 offset:18432
	ds_read_b64_tr_b16 v[164:165], v227 offset:19456
	v_fmamk_f32 v44, v44, 0x3e38aa3b, v234
	v_fmamk_f32 v45, v45, 0x3e38aa3b, v234
	v_fmamk_f32 v46, v46, 0x3e38aa3b, v234
	v_fmamk_f32 v47, v47, 0x3e38aa3b, v234
	v_fmamk_f32 v48, v48, 0x3e38aa3b, v234
	v_fmamk_f32 v49, v49, 0x3e38aa3b, v234
	v_exp_f32_e32 v42, v42
	v_exp_f32_e32 v43, v43
	v_exp_f32_e32 v44, v44
	v_exp_f32_e32 v45, v45
	v_exp_f32_e32 v46, v46
	v_exp_f32_e32 v47, v47
	s_waitcnt lgkmcnt(10)
	v_mfma_f32_32x32x16_bf16 v[86:101], v[130:133], v[106:109], v[86:101]
	ds_read_b64_tr_b16 v[166:167], v228 offset:18432
	ds_read_b64_tr_b16 v[168:169], v228 offset:19456
	v_exp_f32_e32 v48, v48
	v_exp_f32_e32 v49, v49
	v_add_f32_e32 v243, v243, v42
	v_add_f32_e32 v244, v244, v43
	v_add_f32_e32 v245, v245, v44
	v_add_f32_e32 v246, v246, v45
	v_add_f32_e32 v243, v243, v46
	v_add_f32_e32 v244, v244, v47
	v_add_f32_e32 v245, v245, v48
	v_add_f32_e32 v246, v246, v49
	v_cvt_pk_bf16_f32 v42, v42, v43
	v_cvt_pk_bf16_f32 v43, v44, v45
	s_waitcnt lgkmcnt(11)
	v_mfma_f32_32x32x16_bf16 v[70:85], v[134:137], v[110:113], v[70:85]
	ds_read_b64_tr_b16 v[170:171], v227 offset:20480
	ds_read_b64_tr_b16 v[172:173], v227 offset:21504
	v_cvt_pk_bf16_f32 v44, v46, v47
	v_cvt_pk_bf16_f32 v45, v48, v49
	v_fmamk_f32 v50, v50, 0x3e38aa3b, v234
	v_fmamk_f32 v51, v51, 0x3e38aa3b, v234
	v_fmamk_f32 v52, v52, 0x3e38aa3b, v234
	v_fmamk_f32 v53, v53, 0x3e38aa3b, v234
	v_fmamk_f32 v54, v54, 0x3e38aa3b, v234
	v_fmamk_f32 v55, v55, 0x3e38aa3b, v234
	v_fmamk_f32 v56, v56, 0x3e38aa3b, v234
	v_fmamk_f32 v57, v57, 0x3e38aa3b, v234
	v_exp_f32_e32 v50, v50
	v_exp_f32_e32 v51, v51
	s_waitcnt lgkmcnt(12)
	v_mfma_f32_32x32x16_bf16 v[86:101], v[138:141], v[110:113], v[86:101]
	ds_read_b64_tr_b16 v[174:175], v228 offset:20480
	ds_read_b64_tr_b16 v[176:177], v228 offset:21504
	v_exp_f32_e32 v52, v52
	v_exp_f32_e32 v53, v53
	v_exp_f32_e32 v54, v54
	v_exp_f32_e32 v55, v55
	v_exp_f32_e32 v56, v56
	v_exp_f32_e32 v57, v57
	v_add_f32_e32 v243, v243, v50
	v_add_f32_e32 v244, v244, v51
	v_add_f32_e32 v245, v245, v52
	v_add_f32_e32 v246, v246, v53
	v_add_f32_e32 v243, v243, v54
	v_add_f32_e32 v244, v244, v55
	s_waitcnt lgkmcnt(13)
	v_mfma_f32_32x32x16_bf16 v[70:85], v[142:145], v[114:117], v[70:85]
	ds_read_b64_tr_b16 v[178:179], v227 offset:22528
	ds_read_b64_tr_b16 v[180:181], v227 offset:23552
	v_add_f32_e32 v245, v245, v56
	v_add_f32_e32 v246, v246, v57
	v_cvt_pk_bf16_f32 v50, v50, v51
	v_cvt_pk_bf16_f32 v51, v52, v53
	v_cvt_pk_bf16_f32 v52, v54, v55
	v_cvt_pk_bf16_f32 v53, v56, v57
	v_fmamk_f32 v58, v58, 0x3e38aa3b, v234
	v_fmamk_f32 v59, v59, 0x3e38aa3b, v234
	v_fmamk_f32 v60, v60, 0x3e38aa3b, v234
	v_fmamk_f32 v61, v61, 0x3e38aa3b, v234
	v_fmamk_f32 v62, v62, 0x3e38aa3b, v234
	v_fmamk_f32 v63, v63, 0x3e38aa3b, v234
	s_waitcnt lgkmcnt(14)
	v_mfma_f32_32x32x16_bf16 v[86:101], v[146:149], v[114:117], v[86:101]
	ds_read_b64_tr_b16 v[182:183], v228 offset:22528
	ds_read_b64_tr_b16 v[184:185], v228 offset:23552
	s_waitcnt lgkmcnt(14)
	v_fmamk_f32 v64, v64, 0x3e38aa3b, v234
	v_fmamk_f32 v65, v65, 0x3e38aa3b, v234
	v_exp_f32_e32 v58, v58
	v_exp_f32_e32 v59, v59
	v_exp_f32_e32 v60, v60
	v_exp_f32_e32 v61, v61
	v_exp_f32_e32 v62, v62
	v_exp_f32_e32 v63, v63
	v_exp_f32_e32 v64, v64
	v_exp_f32_e32 v65, v65
	v_add_f32_e32 v243, v243, v58
	v_add_f32_e32 v244, v244, v59
	v_add_f32_e32 v245, v245, v60
	v_add_f32_e32 v246, v246, v61
	s_waitcnt lgkmcnt(14)
	v_mfma_f32_32x32x16_bf16 v[0:15], v[154:157], v[34:37], v[0:15]
	ds_read_b128 v[118:121], v223 offset:0
	v_add_f32_e32 v243, v243, v62
	v_add_f32_e32 v244, v244, v63
	v_add_f32_e32 v245, v245, v64
	v_add_f32_e32 v246, v246, v65
	v_cvt_pk_bf16_f32 v58, v58, v59
	v_cvt_pk_bf16_f32 v59, v60, v61
	v_cvt_pk_bf16_f32 v60, v62, v63
	v_cvt_pk_bf16_f32 v61, v64, v65
	v_add_f32_e32 v243, v243, v244
	v_add_f32_e32 v245, v245, v246
	v_add_f32_e32 v243, v243, v245
	v_fma_f32 v231, v231, v232, v243
	s_waitcnt lgkmcnt(13)
	v_mfma_f32_32x32x16_bf16 v[16:31], v[158:161], v[34:37], v[16:31]
	ds_read_b128 v[122:125], v223 offset:4096
	v_lshrrev_b32_e32 v249, v229, v204
	v_lshrrev_b32_e32 v250, v229, v205
	v_bfe_i32 v235, v249, 0, 1
	v_bfe_i32 v236, v250, 0, 1
	v_bfe_i32 v237, v249, 1, 1
	v_bfe_i32 v238, v250, 1, 1
	v_bfe_i32 v239, v249, 2, 1
	v_bfe_i32 v240, v250, 2, 1
	v_bfe_i32 v241, v249, 3, 1
	v_bfe_i32 v242, v250, 3, 1
	v_bitop3_b32 v70, v70, s33, v235 bitop3:0xe4
	s_waitcnt lgkmcnt(12)
	v_mfma_f32_32x32x16_bf16 v[0:15], v[162:165], v[42:45], v[0:15]
	ds_read_b128 v[126:129], v224 offset:0
	v_bitop3_b32 v86, v86, s33, v236 bitop3:0xe4
	v_bitop3_b32 v71, v71, s33, v237 bitop3:0xe4
	v_bitop3_b32 v87, v87, s33, v238 bitop3:0xe4
	v_bitop3_b32 v72, v72, s33, v239 bitop3:0xe4
	v_bitop3_b32 v88, v88, s33, v240 bitop3:0xe4
	v_bitop3_b32 v73, v73, s33, v241 bitop3:0xe4
	v_bitop3_b32 v89, v89, s33, v242 bitop3:0xe4
	v_max3_f32 v247, v70, s33, v86
	v_max3_f32 v248, v71, s33, v87
	v_max3_f32 v247, v247, v72, v88
	v_max3_f32 v248, v248, v73, v89
	v_bfe_i32 v235, v249, 8, 1
	s_waitcnt lgkmcnt(11)
	v_mfma_f32_32x32x16_bf16 v[16:31], v[166:169], v[42:45], v[16:31]
	ds_read_b128 v[130:133], v224 offset:4096
	v_bfe_i32 v236, v250, 8, 1
	v_bfe_i32 v237, v249, 9, 1
	v_bfe_i32 v238, v250, 9, 1
	v_bfe_i32 v239, v249, 10, 1
	v_bfe_i32 v240, v250, 10, 1
	v_bfe_i32 v241, v249, 11, 1
	v_bfe_i32 v242, v250, 11, 1
	v_bitop3_b32 v74, v74, s33, v235 bitop3:0xe4
	v_bitop3_b32 v90, v90, s33, v236 bitop3:0xe4
	v_bitop3_b32 v75, v75, s33, v237 bitop3:0xe4
	v_bitop3_b32 v91, v91, s33, v238 bitop3:0xe4
	v_bitop3_b32 v76, v76, s33, v239 bitop3:0xe4
	s_waitcnt lgkmcnt(10)
	v_mfma_f32_32x32x16_bf16 v[0:15], v[170:173], v[50:53], v[0:15]
	ds_read_b128 v[134:137], v225 offset:0
	v_bitop3_b32 v92, v92, s33, v240 bitop3:0xe4
	v_bitop3_b32 v77, v77, s33, v241 bitop3:0xe4
	v_bitop3_b32 v93, v93, s33, v242 bitop3:0xe4
	v_max3_f32 v247, v247, v74, v90
	v_max3_f32 v248, v248, v75, v91
	v_max3_f32 v247, v247, v76, v92
	v_max3_f32 v248, v248, v77, v93
	v_bfe_i32 v235, v249, 16, 1
	v_bfe_i32 v236, v250, 16, 1
	v_bfe_i32 v237, v249, 17, 1
	v_bfe_i32 v238, v250, 17, 1
	v_bfe_i32 v239, v249, 18, 1
	s_waitcnt lgkmcnt(9)
	v_mfma_f32_32x32x16_bf16 v[16:31], v[174:177], v[50:53], v[16:31]
	ds_read_b128 v[138:141], v225 offset:4096
	v_bfe_i32 v240, v250, 18, 1
	v_bfe_i32 v241, v249, 19, 1
	v_bfe_i32 v242, v250, 19, 1
	v_bitop3_b32 v78, v78, s33, v235 bitop3:0xe4
	v_bitop3_b32 v94, v94, s33, v236 bitop3:0xe4
	v_bitop3_b32 v79, v79, s33, v237 bitop3:0xe4
	v_bitop3_b32 v95, v95, s33, v238 bitop3:0xe4
	v_bitop3_b32 v80, v80, s33, v239 bitop3:0xe4
	v_bitop3_b32 v96, v96, s33, v240 bitop3:0xe4
	v_bitop3_b32 v81, v81, s33, v241 bitop3:0xe4
	v_bitop3_b32 v97, v97, s33, v242 bitop3:0xe4
	v_max3_f32 v247, v247, v78, v94
	s_waitcnt lgkmcnt(8)
	v_mfma_f32_32x32x16_bf16 v[0:15], v[178:181], v[58:61], v[0:15]
	ds_read_b128 v[142:145], v226 offset:0
	v_max3_f32 v248, v248, v79, v95
	v_max3_f32 v247, v247, v80, v96
	v_max3_f32 v248, v248, v81, v97
	v_bfe_i32 v235, v249, 24, 1
	v_bfe_i32 v236, v250, 24, 1
	v_bfe_i32 v237, v249, 25, 1
	v_bfe_i32 v238, v250, 25, 1
	v_bfe_i32 v239, v249, 26, 1
	v_bfe_i32 v240, v250, 26, 1
	v_bfe_i32 v241, v249, 27, 1
	v_bfe_i32 v242, v250, 27, 1
	v_bitop3_b32 v82, v82, s33, v235 bitop3:0xe4
	s_waitcnt lgkmcnt(7)
	v_mfma_f32_32x32x16_bf16 v[16:31], v[182:185], v[58:61], v[16:31]
	ds_read_b128 v[146:149], v226 offset:4096
	v_bitop3_b32 v98, v98, s33, v236 bitop3:0xe4
	v_bitop3_b32 v83, v83, s33, v237 bitop3:0xe4
	v_bitop3_b32 v99, v99, s33, v238 bitop3:0xe4
	v_bitop3_b32 v84, v84, s33, v239 bitop3:0xe4
	v_bitop3_b32 v100, v100, s33, v240 bitop3:0xe4
	v_bitop3_b32 v85, v85, s33, v241 bitop3:0xe4
	v_bitop3_b32 v101, v101, s33, v242 bitop3:0xe4
	v_max3_f32 v247, v247, v82, v98
	v_max3_f32 v248, v248, v83, v99
	v_max3_f32 v247, v247, v84, v100
	v_max3_f32 v248, v248, v85, v101
	v_max_f32_e32 v247, v247, v248
	v_mov_b32_e32 v248, v247
	s_nop 1
	v_permlane32_swap_b32_e32 v247, v248
	v_max3_f32 v247, v230, v247, v248
	v_cmp_neq_f32_e32 vcc, s33, v247
	s_nop 1
	v_cndmask_b32_e32 v248, 0, v247, vcc
	v_sub_f32_e32 v33, v230, v248
	v_mul_f32_e32 v33, 0x3e38aa3b, v33
	v_exp_f32_e32 v232, v33
	v_mul_f32_e32 v234, 0xbe38aa3b, v248
	v_mov_b32_e32 v230, v247
	s_waitcnt vmcnt(3)
	s_barrier
	s_add_u32 s8, s8, 1
	s_cmp_lt_u32 s8, s9
	s_cbranch_scc1 .Lat_loop_3
	s_branch .Lat_epilogue

.Lat_loop_3:
	s_add_u32 s18, s8, 4
	s_min_u32 s18, s18, s11
	s_mul_i32 s18, s18, 0xb2c00
	s_add_u32 s12, s4, s18
	s_addc_u32 s13, s5, 0
	s_add_u32 s19, s8, 2
	s_min_u32 s19, s19, s11
	s_mul_i32 s18, s19, 0xb2c00
	s_add_u32 s14, s4, s18
	s_addc_u32 s15, s5, 0
	s_add_i32 m0, s58, 0x6000
	s_nop 0
	global_load_lds_dwordx4 v221, s[12:13]
	s_add_i32 m0, s58, 0xa000
	s_nop 0
	global_load_lds_dwordx4 v222, s[14:15]
	s_cmp_lt_u32 s8, s10
	s_cbranch_scc1 .Lat_full_3
	s_cmp_eq_u32 s8, s10
	s_cbranch_scc1 .Lat_last_3

.Lat_nors_f3:
	v_fmamk_f32 v70, v70, 0x3e38aa3b, v234
	v_fmamk_f32 v71, v71, 0x3e38aa3b, v234
	s_waitcnt lgkmcnt(7)
	v_mfma_f32_32x32x16_bf16 v[34:49], v[118:121], v[102:105], 0
	ds_read_b64_tr_b16 v[154:155], v227 offset:24576
	ds_read_b64_tr_b16 v[156:157], v227 offset:25600
	v_fmamk_f32 v72, v72, 0x3e38aa3b, v234
	v_fmamk_f32 v73, v73, 0x3e38aa3b, v234
	v_fmamk_f32 v74, v74, 0x3e38aa3b, v234
	v_fmamk_f32 v75, v75, 0x3e38aa3b, v234
	v_fmamk_f32 v76, v76, 0x3e38aa3b, v234
	v_fmamk_f32 v77, v77, 0x3e38aa3b, v234
	v_exp_f32_e32 v70, v70
	v_exp_f32_e32 v71, v71
	v_exp_f32_e32 v72, v72
	v_exp_f32_e32 v73, v73
	v_exp_f32_e32 v74, v74
	v_exp_f32_e32 v75, v75
	s_waitcnt lgkmcnt(8)
	v_mfma_f32_32x32x16_bf16 v[50:65], v[122:125], v[102:105], 0
	ds_read_b64_tr_b16 v[158:159], v228 offset:24576
	ds_read_b64_tr_b16 v[160:161], v228 offset:25600
	v_exp_f32_e32 v76, v76
	v_exp_f32_e32 v77, v77
	v_add_f32_e32 v243, v70, v74
	v_add_f32_e32 v244, v71, v75
	v_add_f32_e32 v245, v72, v76
	v_add_f32_e32 v246, v73, v77
	v_cvt_pk_bf16_f32 v70, v70, v71
	v_cvt_pk_bf16_f32 v71, v72, v73
	v_cvt_pk_bf16_f32 v72, v74, v75
	v_cvt_pk_bf16_f32 v73, v76, v77
	v_fmamk_f32 v78, v78, 0x3e38aa3b, v234
	v_fmamk_f32 v79, v79, 0x3e38aa3b, v234
	s_waitcnt lgkmcnt(9)
	v_mfma_f32_32x32x16_bf16 v[34:49], v[126:129], v[106:109], v[34:49]
	ds_read_b64_tr_b16 v[162:163], v227 offset:26624
	ds_read_b64_tr_b16 v[164:165], v227 offset:27648
	v_fmamk_f32 v80, v80, 0x3e38aa3b, v234
	v_fmamk_f32 v81, v81, 0x3e38aa3b, v234
	v_fmamk_f32 v82, v82, 0x3e38aa3b, v234
	v_fmamk_f32 v83, v83, 0x3e38aa3b, v234
	v_fmamk_f32 v84, v84, 0x3e38aa3b, v234
	v_fmamk_f32 v85, v85, 0x3e38aa3b, v234
	v_exp_f32_e32 v78, v78
	v_exp_f32_e32 v79, v79
	v_exp_f32_e32 v80, v80
	v_exp_f32_e32 v81, v81
	v_exp_f32_e32 v82, v82
	v_exp_f32_e32 v83, v83
	s_waitcnt lgkmcnt(10)
	v_mfma_f32_32x32x16_bf16 v[50:65], v[130:133], v[106:109], v[50:65]
	ds_read_b64_tr_b16 v[166:167], v228 offset:26624
	ds_read_b64_tr_b16 v[168:169], v228 offset:27648
	v_exp_f32_e32 v84, v84
	v_exp_f32_e32 v85, v85
	v_add_f32_e32 v243, v243, v78
	v_add_f32_e32 v244, v244, v79
	v_add_f32_e32 v245, v245, v80
	v_add_f32_e32 v246, v246, v81
	v_add_f32_e32 v243, v243, v82
	v_add_f32_e32 v244, v244, v83
	v_add_f32_e32 v245, v245, v84
	v_add_f32_e32 v246, v246, v85
	v_cvt_pk_bf16_f32 v78, v78, v79
	v_cvt_pk_bf16_f32 v79, v80, v81
	s_waitcnt lgkmcnt(11)
	v_mfma_f32_32x32x16_bf16 v[34:49], v[134:137], v[110:113], v[34:49]
	ds_read_b64_tr_b16 v[170:171], v227 offset:28672
	ds_read_b64_tr_b16 v[172:173], v227 offset:29696
	v_cvt_pk_bf16_f32 v80, v82, v83
	v_cvt_pk_bf16_f32 v81, v84, v85
	v_fmamk_f32 v86, v86, 0x3e38aa3b, v234
	v_fmamk_f32 v87, v87, 0x3e38aa3b, v234
	v_fmamk_f32 v88, v88, 0x3e38aa3b, v234
	v_fmamk_f32 v89, v89, 0x3e38aa3b, v234
	v_fmamk_f32 v90, v90, 0x3e38aa3b, v234
	v_fmamk_f32 v91, v91, 0x3e38aa3b, v234
	v_fmamk_f32 v92, v92, 0x3e38aa3b, v234
	v_fmamk_f32 v93, v93, 0x3e38aa3b, v234
	v_exp_f32_e32 v86, v86
	v_exp_f32_e32 v87, v87
	s_waitcnt lgkmcnt(12)
	v_mfma_f32_32x32x16_bf16 v[50:65], v[138:141], v[110:113], v[50:65]
	ds_read_b64_tr_b16 v[174:175], v228 offset:28672
	ds_read_b64_tr_b16 v[176:177], v228 offset:29696
	v_exp_f32_e32 v88, v88
	v_exp_f32_e32 v89, v89
	v_exp_f32_e32 v90, v90
	v_exp_f32_e32 v91, v91
	v_exp_f32_e32 v92, v92
	v_exp_f32_e32 v93, v93
	v_add_f32_e32 v243, v243, v86
	v_add_f32_e32 v244, v244, v87
	v_add_f32_e32 v245, v245, v88
	v_add_f32_e32 v246, v246, v89
	v_add_f32_e32 v243, v243, v90
	v_add_f32_e32 v244, v244, v91
	s_waitcnt lgkmcnt(13)
	v_mfma_f32_32x32x16_bf16 v[34:49], v[142:145], v[114:117], v[34:49]
	ds_read_b64_tr_b16 v[178:179], v227 offset:30720
	ds_read_b64_tr_b16 v[180:181], v227 offset:31744
	v_add_f32_e32 v245, v245, v92
	v_add_f32_e32 v246, v246, v93
	v_cvt_pk_bf16_f32 v86, v86, v87
	v_cvt_pk_bf16_f32 v87, v88, v89
	v_cvt_pk_bf16_f32 v88, v90, v91
	v_cvt_pk_bf16_f32 v89, v92, v93
	v_fmamk_f32 v94, v94, 0x3e38aa3b, v234
	v_fmamk_f32 v95, v95, 0x3e38aa3b, v234
	v_fmamk_f32 v96, v96, 0x3e38aa3b, v234
	v_fmamk_f32 v97, v97, 0x3e38aa3b, v234
	v_fmamk_f32 v98, v98, 0x3e38aa3b, v234
	v_fmamk_f32 v99, v99, 0x3e38aa3b, v234
	s_waitcnt lgkmcnt(14)
	v_mfma_f32_32x32x16_bf16 v[50:65], v[146:149], v[114:117], v[50:65]
	ds_read_b64_tr_b16 v[182:183], v228 offset:30720
	ds_read_b64_tr_b16 v[184:185], v228 offset:31744
	s_waitcnt lgkmcnt(14)
	v_fmamk_f32 v100, v100, 0x3e38aa3b, v234
	v_fmamk_f32 v101, v101, 0x3e38aa3b, v234
	v_exp_f32_e32 v94, v94
	v_exp_f32_e32 v95, v95
	v_exp_f32_e32 v96, v96
	v_exp_f32_e32 v97, v97
	v_exp_f32_e32 v98, v98
	v_exp_f32_e32 v99, v99
	v_exp_f32_e32 v100, v100
	v_exp_f32_e32 v101, v101
	v_add_f32_e32 v243, v243, v94
	v_add_f32_e32 v244, v244, v95
	v_add_f32_e32 v245, v245, v96
	v_add_f32_e32 v246, v246, v97
	s_waitcnt lgkmcnt(14)
	v_mfma_f32_32x32x16_bf16 v[0:15], v[154:157], v[70:73], v[0:15]
	ds_read_b128 v[118:121], v223 offset:8192
	v_add_f32_e32 v243, v243, v98
	v_add_f32_e32 v244, v244, v99
	v_add_f32_e32 v245, v245, v100
	v_add_f32_e32 v246, v246, v101
	v_cvt_pk_bf16_f32 v94, v94, v95
	v_cvt_pk_bf16_f32 v95, v96, v97
	v_cvt_pk_bf16_f32 v96, v98, v99
	v_cvt_pk_bf16_f32 v97, v100, v101
	v_add_f32_e32 v243, v243, v244
	v_add_f32_e32 v245, v245, v246
	v_add_f32_e32 v243, v243, v245
	v_fma_f32 v231, v231, v232, v243
	s_waitcnt lgkmcnt(13)
	v_mfma_f32_32x32x16_bf16 v[16:31], v[158:161], v[70:73], v[16:31]
	ds_read_b128 v[122:125], v223 offset:12288
	s_waitcnt vmcnt(4)
	v_lshrrev_b32_e32 v249, v229, v198
	v_lshrrev_b32_e32 v250, v229, v199
	v_bfe_i32 v235, v249, 0, 1
	v_bfe_i32 v236, v250, 0, 1
	v_bfe_i32 v237, v249, 1, 1
	v_bfe_i32 v238, v250, 1, 1
	v_bfe_i32 v239, v249, 2, 1
	v_bfe_i32 v240, v250, 2, 1
	v_bfe_i32 v241, v249, 3, 1
	v_bfe_i32 v242, v250, 3, 1
	v_bitop3_b32 v34, v34, s33, v235 bitop3:0xe4
	s_waitcnt lgkmcnt(12)
	v_mfma_f32_32x32x16_bf16 v[0:15], v[162:165], v[78:81], v[0:15]
	ds_read_b128 v[126:129], v224 offset:8192
	v_bitop3_b32 v50, v50, s33, v236 bitop3:0xe4
	v_bitop3_b32 v35, v35, s33, v237 bitop3:0xe4
	v_bitop3_b32 v51, v51, s33, v238 bitop3:0xe4
	v_bitop3_b32 v36, v36, s33, v239 bitop3:0xe4
	v_bitop3_b32 v52, v52, s33, v240 bitop3:0xe4
	v_bitop3_b32 v37, v37, s33, v241 bitop3:0xe4
	v_bitop3_b32 v53, v53, s33, v242 bitop3:0xe4
	v_max3_f32 v247, v34, s33, v50
	v_max3_f32 v248, v35, s33, v51
	v_max3_f32 v247, v247, v36, v52
	v_max3_f32 v248, v248, v37, v53
	v_bfe_i32 v235, v249, 8, 1
	s_waitcnt lgkmcnt(11)
	v_mfma_f32_32x32x16_bf16 v[16:31], v[166:169], v[78:81], v[16:31]
	ds_read_b128 v[130:133], v224 offset:12288
	v_bfe_i32 v236, v250, 8, 1
	v_bfe_i32 v237, v249, 9, 1
	v_bfe_i32 v238, v250, 9, 1
	v_bfe_i32 v239, v249, 10, 1
	v_bfe_i32 v240, v250, 10, 1
	v_bfe_i32 v241, v249, 11, 1
	v_bfe_i32 v242, v250, 11, 1
	v_bitop3_b32 v38, v38, s33, v235 bitop3:0xe4
	v_bitop3_b32 v54, v54, s33, v236 bitop3:0xe4
	v_bitop3_b32 v39, v39, s33, v237 bitop3:0xe4
	v_bitop3_b32 v55, v55, s33, v238 bitop3:0xe4
	v_bitop3_b32 v40, v40, s33, v239 bitop3:0xe4
	s_waitcnt lgkmcnt(10)
	v_mfma_f32_32x32x16_bf16 v[0:15], v[170:173], v[86:89], v[0:15]
	ds_read_b128 v[134:137], v225 offset:8192
	v_bitop3_b32 v56, v56, s33, v240 bitop3:0xe4
	v_bitop3_b32 v41, v41, s33, v241 bitop3:0xe4
	v_bitop3_b32 v57, v57, s33, v242 bitop3:0xe4
	v_max3_f32 v247, v247, v38, v54
	v_max3_f32 v248, v248, v39, v55
	v_max3_f32 v247, v247, v40, v56
	v_max3_f32 v248, v248, v41, v57
	v_bfe_i32 v235, v249, 16, 1
	v_bfe_i32 v236, v250, 16, 1
	v_bfe_i32 v237, v249, 17, 1
	v_bfe_i32 v238, v250, 17, 1
	v_bfe_i32 v239, v249, 18, 1
	s_waitcnt lgkmcnt(9)
	v_mfma_f32_32x32x16_bf16 v[16:31], v[174:177], v[86:89], v[16:31]
	ds_read_b128 v[138:141], v225 offset:12288
	v_bfe_i32 v240, v250, 18, 1
	v_bfe_i32 v241, v249, 19, 1
	v_bfe_i32 v242, v250, 19, 1
	v_bitop3_b32 v42, v42, s33, v235 bitop3:0xe4
	v_bitop3_b32 v58, v58, s33, v236 bitop3:0xe4
	v_bitop3_b32 v43, v43, s33, v237 bitop3:0xe4
	v_bitop3_b32 v59, v59, s33, v238 bitop3:0xe4
	v_bitop3_b32 v44, v44, s33, v239 bitop3:0xe4
	v_bitop3_b32 v60, v60, s33, v240 bitop3:0xe4
	v_bitop3_b32 v45, v45, s33, v241 bitop3:0xe4
	v_bitop3_b32 v61, v61, s33, v242 bitop3:0xe4
	v_max3_f32 v247, v247, v42, v58
	s_waitcnt lgkmcnt(8)
	v_mfma_f32_32x32x16_bf16 v[0:15], v[178:181], v[94:97], v[0:15]
	ds_read_b128 v[142:145], v226 offset:8192
	v_max3_f32 v248, v248, v43, v59
	v_max3_f32 v247, v247, v44, v60
	v_max3_f32 v248, v248, v45, v61
	v_bfe_i32 v235, v249, 24, 1
	v_bfe_i32 v236, v250, 24, 1
	v_bfe_i32 v237, v249, 25, 1
	v_bfe_i32 v238, v250, 25, 1
	v_bfe_i32 v239, v249, 26, 1
	v_bfe_i32 v240, v250, 26, 1
	v_bfe_i32 v241, v249, 27, 1
	v_bfe_i32 v242, v250, 27, 1
	v_bitop3_b32 v46, v46, s33, v235 bitop3:0xe4
	s_waitcnt lgkmcnt(7)
	v_mfma_f32_32x32x16_bf16 v[16:31], v[182:185], v[94:97], v[16:31]
	ds_read_b128 v[146:149], v226 offset:12288
	v_bitop3_b32 v62, v62, s33, v236 bitop3:0xe4
	v_bitop3_b32 v47, v47, s33, v237 bitop3:0xe4
	v_bitop3_b32 v63, v63, s33, v238 bitop3:0xe4
	v_bitop3_b32 v48, v48, s33, v239 bitop3:0xe4
	v_bitop3_b32 v64, v64, s33, v240 bitop3:0xe4
	v_bitop3_b32 v49, v49, s33, v241 bitop3:0xe4
	v_bitop3_b32 v65, v65, s33, v242 bitop3:0xe4
	v_max3_f32 v247, v247, v46, v62
	v_max3_f32 v248, v248, v47, v63
	v_max3_f32 v247, v247, v48, v64
	v_max3_f32 v248, v248, v49, v65
	v_max_f32_e32 v247, v247, v248
	v_mov_b32_e32 v248, v247
	s_nop 1
	v_permlane32_swap_b32_e32 v247, v248
	v_max3_f32 v247, v230, v247, v248
	v_cmp_neq_f32_e32 vcc, s33, v247
	s_nop 1
	v_cndmask_b32_e32 v248, 0, v247, vcc
	v_sub_f32_e32 v33, v230, v248
	v_mul_f32_e32 v33, 0x3e38aa3b, v33
	v_exp_f32_e32 v232, v33
	v_mul_f32_e32 v234, 0xbe38aa3b, v248
	v_mov_b32_e32 v230, v247
	s_waitcnt vmcnt(2)
	s_barrier
	s_add_u32 s8, s8, 1
	s_cmp_lt_u32 s8, s9
	s_cbranch_scc1 .Lat_loop_0
	s_branch .Lat_epilogue

.Lat_nors_l3:
	v_fmamk_f32 v70, v70, 0x3e38aa3b, v234
	v_fmamk_f32 v71, v71, 0x3e38aa3b, v234
	v_fmamk_f32 v72, v72, 0x3e38aa3b, v234
	ds_read_b64_tr_b16 v[168:169], v228 offset:27648
	s_waitcnt lgkmcnt(14)
	v_fmamk_f32 v73, v73, 0x3e38aa3b, v234
	v_fmamk_f32 v74, v74, 0x3e38aa3b, v234
	v_fmamk_f32 v75, v75, 0x3e38aa3b, v234
	ds_read_b64_tr_b16 v[170:171], v227 offset:28672
	s_waitcnt lgkmcnt(14)
	v_fmamk_f32 v76, v76, 0x3e38aa3b, v234
	v_fmamk_f32 v77, v77, 0x3e38aa3b, v234
	v_exp_f32_e32 v70, v70
	ds_read_b64_tr_b16 v[172:173], v227 offset:29696
	s_waitcnt lgkmcnt(14)
	v_exp_f32_e32 v71, v71
	v_exp_f32_e32 v72, v72
	v_exp_f32_e32 v73, v73
	ds_read_b64_tr_b16 v[174:175], v228 offset:28672
	s_waitcnt lgkmcnt(14)
	v_exp_f32_e32 v74, v74
	v_exp_f32_e32 v75, v75
	v_exp_f32_e32 v76, v76
	ds_read_b64_tr_b16 v[176:177], v228 offset:29696
	s_waitcnt lgkmcnt(14)
	v_exp_f32_e32 v77, v77
	v_add_f32_e32 v243, v70, v74
	v_add_f32_e32 v244, v71, v75
	ds_read_b64_tr_b16 v[178:179], v227 offset:30720
	s_waitcnt lgkmcnt(14)
	v_add_f32_e32 v245, v72, v76
	v_add_f32_e32 v246, v73, v77
	v_cvt_pk_bf16_f32 v70, v70, v71
	ds_read_b64_tr_b16 v[180:181], v227 offset:31744
	s_waitcnt lgkmcnt(14)
	v_cvt_pk_bf16_f32 v71, v72, v73
	v_cvt_pk_bf16_f32 v72, v74, v75
	v_cvt_pk_bf16_f32 v73, v76, v77
	ds_read_b64_tr_b16 v[182:183], v228 offset:30720
	s_waitcnt lgkmcnt(14)
	s_waitcnt lgkmcnt(13)
	v_mfma_f32_32x32x16_bf16 v[0:15], v[154:157], v[70:73], v[0:15]
	s_waitcnt lgkmcnt(11)
	v_mfma_f32_32x32x16_bf16 v[16:31], v[158:161], v[70:73], v[16:31]
	v_fmamk_f32 v78, v78, 0x3e38aa3b, v234
	v_fmamk_f32 v79, v79, 0x3e38aa3b, v234
	v_fmamk_f32 v80, v80, 0x3e38aa3b, v234
	ds_read_b64_tr_b16 v[184:185], v228 offset:31744
	v_fmamk_f32 v81, v81, 0x3e38aa3b, v234
	v_fmamk_f32 v82, v82, 0x3e38aa3b, v234
	v_fmamk_f32 v83, v83, 0x3e38aa3b, v234
	v_fmamk_f32 v84, v84, 0x3e38aa3b, v234
	v_fmamk_f32 v85, v85, 0x3e38aa3b, v234
	v_exp_f32_e32 v78, v78
	v_exp_f32_e32 v79, v79
	v_exp_f32_e32 v80, v80
	v_exp_f32_e32 v81, v81
	v_exp_f32_e32 v82, v82
	v_exp_f32_e32 v83, v83
	v_exp_f32_e32 v84, v84
	v_exp_f32_e32 v85, v85
	v_add_f32_e32 v243, v243, v78
	v_add_f32_e32 v244, v244, v79
	v_add_f32_e32 v245, v245, v80
	v_add_f32_e32 v246, v246, v81
	v_add_f32_e32 v243, v243, v82
	v_add_f32_e32 v244, v244, v83
	v_add_f32_e32 v245, v245, v84
	v_add_f32_e32 v246, v246, v85
	v_cvt_pk_bf16_f32 v78, v78, v79
	v_cvt_pk_bf16_f32 v79, v80, v81
	v_cvt_pk_bf16_f32 v80, v82, v83
	v_cvt_pk_bf16_f32 v81, v84, v85
	s_waitcnt lgkmcnt(10)
	v_mfma_f32_32x32x16_bf16 v[0:15], v[162:165], v[78:81], v[0:15]
	s_waitcnt lgkmcnt(8)
	v_mfma_f32_32x32x16_bf16 v[16:31], v[166:169], v[78:81], v[16:31]
	v_fmamk_f32 v86, v86, 0x3e38aa3b, v234
	v_fmamk_f32 v87, v87, 0x3e38aa3b, v234
	v_fmamk_f32 v88, v88, 0x3e38aa3b, v234
	v_fmamk_f32 v89, v89, 0x3e38aa3b, v234
	v_fmamk_f32 v90, v90, 0x3e38aa3b, v234
	v_fmamk_f32 v91, v91, 0x3e38aa3b, v234
	v_fmamk_f32 v92, v92, 0x3e38aa3b, v234
	v_fmamk_f32 v93, v93, 0x3e38aa3b, v234
	v_exp_f32_e32 v86, v86
	v_exp_f32_e32 v87, v87
	v_exp_f32_e32 v88, v88
	v_exp_f32_e32 v89, v89
	v_exp_f32_e32 v90, v90
	v_exp_f32_e32 v91, v91
	v_exp_f32_e32 v92, v92
	v_exp_f32_e32 v93, v93
	v_add_f32_e32 v243, v243, v86
	v_add_f32_e32 v244, v244, v87
	v_add_f32_e32 v245, v245, v88
	v_add_f32_e32 v246, v246, v89
	v_add_f32_e32 v243, v243, v90
	v_add_f32_e32 v244, v244, v91
	v_add_f32_e32 v245, v245, v92
	v_add_f32_e32 v246, v246, v93
	v_cvt_pk_bf16_f32 v86, v86, v87
	v_cvt_pk_bf16_f32 v87, v88, v89
	v_cvt_pk_bf16_f32 v88, v90, v91
	v_cvt_pk_bf16_f32 v89, v92, v93
	s_waitcnt lgkmcnt(6)
	v_mfma_f32_32x32x16_bf16 v[0:15], v[170:173], v[86:89], v[0:15]
	s_waitcnt lgkmcnt(4)
	v_mfma_f32_32x32x16_bf16 v[16:31], v[174:177], v[86:89], v[16:31]
	v_fmamk_f32 v94, v94, 0x3e38aa3b, v234
	v_fmamk_f32 v95, v95, 0x3e38aa3b, v234
	v_fmamk_f32 v96, v96, 0x3e38aa3b, v234
	v_fmamk_f32 v97, v97, 0x3e38aa3b, v234
	v_fmamk_f32 v98, v98, 0x3e38aa3b, v234
	v_fmamk_f32 v99, v99, 0x3e38aa3b, v234
	v_fmamk_f32 v100, v100, 0x3e38aa3b, v234
	v_fmamk_f32 v101, v101, 0x3e38aa3b, v234
	v_exp_f32_e32 v94, v94
	v_exp_f32_e32 v95, v95
	v_exp_f32_e32 v96, v96
	v_exp_f32_e32 v97, v97
	v_exp_f32_e32 v98, v98
	v_exp_f32_e32 v99, v99
	v_exp_f32_e32 v100, v100
	v_exp_f32_e32 v101, v101
	v_add_f32_e32 v243, v243, v94
	v_add_f32_e32 v244, v244, v95
	v_add_f32_e32 v245, v245, v96
	v_add_f32_e32 v246, v246, v97
	v_add_f32_e32 v243, v243, v98
	v_add_f32_e32 v244, v244, v99
	v_add_f32_e32 v245, v245, v100
	v_add_f32_e32 v246, v246, v101
	v_cvt_pk_bf16_f32 v94, v94, v95
	v_cvt_pk_bf16_f32 v95, v96, v97
	v_cvt_pk_bf16_f32 v96, v98, v99
	v_cvt_pk_bf16_f32 v97, v100, v101
	v_add_f32_e32 v243, v243, v244
	v_add_f32_e32 v245, v245, v246
	v_add_f32_e32 v243, v243, v245
	v_fma_f32 v231, v231, v232, v243
	s_waitcnt lgkmcnt(2)
	v_mfma_f32_32x32x16_bf16 v[0:15], v[178:181], v[94:97], v[0:15]
	s_waitcnt lgkmcnt(0)
	v_mfma_f32_32x32x16_bf16 v[16:31], v[182:185], v[94:97], v[16:31]
	s_waitcnt vmcnt(2)
	s_barrier
	s_add_u32 s8, s8, 1
	s_cmp_lt_u32 s8, s9
	s_cbranch_scc1 .Lat_loop_0
	s_branch .Lat_epilogue

.Lat_exit:
	s_setprio 0
	s_waitcnt vmcnt(0)
	s_mov_b32 s58, s84
	s_movk_i32 s83, 0x2cb0
	s_branch .LBB0_829
